# S5 step loops: broadcast movs folded into op_sel, packed bf16 convert, LDS offsets folded
# speedup vs baseline: 1.0085x; 1.0085x over previous
.LBB0_279:
	v_add_u32_e32 v41, s4, v35
	ds_read_b128 v[110:113], v41
	ds_read_b128 v[114:117], v41 offset:16
	ds_read_b128 v[118:121], v41 offset:32
	ds_read_b128 v[122:125], v41 offset:48
	s_addk_i32 s4, 0x200
	s_waitcnt lgkmcnt(3)
	v_pk_fma_f32 v[126:127], v[110:111], v[108:109], 0 op_sel_hi:[0,1,0]
	v_pk_fma_f32 v[110:111], v[110:111], v[28:29], v[126:127] op_sel:[1,0,0]
	s_cmpk_lg_i32 s4, 0x1000
	v_pk_fma_f32 v[110:111], v[112:113], v[24:25], v[110:111] op_sel_hi:[0,1,1]
	v_pk_fma_f32 v[110:111], v[112:113], v[26:27], v[110:111] op_sel:[1,0,0]
	s_waitcnt lgkmcnt(2)
	v_pk_fma_f32 v[110:111], v[114:115], v[30:31], v[110:111] op_sel_hi:[0,1,1]
	v_pk_fma_f32 v[110:111], v[114:115], v[20:21], v[110:111] op_sel:[1,0,0]
	v_pk_fma_f32 v[110:111], v[116:117], v[16:17], v[110:111] op_sel_hi:[0,1,1]
	v_pk_fma_f32 v[110:111], v[116:117], v[18:19], v[110:111] op_sel:[1,0,0]
	s_waitcnt lgkmcnt(1)
	v_pk_fma_f32 v[110:111], v[118:119], v[22:23], v[110:111] op_sel_hi:[0,1,1]
	v_pk_fma_f32 v[110:111], v[118:119], v[12:13], v[110:111] op_sel:[1,0,0]
	v_pk_fma_f32 v[110:111], v[120:121], v[8:9], v[110:111] op_sel_hi:[0,1,1]
	v_pk_fma_f32 v[110:111], v[120:121], v[10:11], v[110:111] op_sel:[1,0,0]
	s_waitcnt lgkmcnt(0)
	v_pk_fma_f32 v[110:111], v[122:123], v[14:15], v[110:111] op_sel_hi:[0,1,1]
	v_pk_fma_f32 v[110:111], v[122:123], v[4:5], v[110:111] op_sel:[1,0,0]
	v_pk_mul_f32 v[112:113], v[106:107], v[6:7] op_sel:[0,1] op_sel_hi:[1,0]
	v_pk_fma_f32 v[110:111], v[124:125], v[0:1], v[110:111] op_sel_hi:[0,1,1]
	v_pk_fma_f32 v[110:111], v[124:125], v[2:3], v[110:111] op_sel:[1,0,0]
	v_pk_fma_f32 v[114:115], v[104:105], v[6:7], v[112:113] neg_lo:[0,0,1] neg_hi:[0,0,1]
	v_pk_fma_f32 v[6:7], v[104:105], v[6:7], v[112:113]
	s_nop 0
	v_mov_b32_e32 v115, v7
	v_pk_add_f32 v[6:7], v[114:115], v[110:111]
	ds_read_b128 v[110:113], v41 offset:64
	ds_read_b128 v[114:117], v41 offset:80
	v_pk_mul_f32 v[122:123], v[106:107], v[6:7] op_sel:[0,1] op_sel_hi:[1,0]
	s_waitcnt lgkmcnt(1)
	v_pk_fma_f32 v[118:119], v[110:111], v[108:109], 0 op_sel_hi:[0,1,0]
	v_pk_fma_f32 v[110:111], v[110:111], v[28:29], v[118:119] op_sel:[1,0,0]
	s_nop 0
	v_pk_fma_f32 v[110:111], v[112:113], v[24:25], v[110:111] op_sel_hi:[0,1,1]
	v_pk_fma_f32 v[110:111], v[112:113], v[26:27], v[110:111] op_sel:[1,0,0]
	s_waitcnt lgkmcnt(0)
	v_pk_fma_f32 v[110:111], v[114:115], v[30:31], v[110:111] op_sel_hi:[0,1,1]
	v_pk_fma_f32 v[114:115], v[114:115], v[20:21], v[110:111] op_sel:[1,0,0]
	ds_read_b128 v[110:113], v41 offset:96
	ds_read_b128 v[118:121], v41 offset:112
	v_pk_fma_f32 v[114:115], v[116:117], v[16:17], v[114:115] op_sel_hi:[0,1,1]
	v_pk_fma_f32 v[114:115], v[116:117], v[18:19], v[114:115] op_sel:[1,0,0]
	s_waitcnt lgkmcnt(1)
	v_pk_fma_f32 v[114:115], v[110:111], v[22:23], v[114:115] op_sel_hi:[0,1,1]
	v_pk_fma_f32 v[110:111], v[110:111], v[12:13], v[114:115] op_sel:[1,0,0]
	s_nop 0
	v_pk_fma_f32 v[110:111], v[112:113], v[8:9], v[110:111] op_sel_hi:[0,1,1]
	v_pk_fma_f32 v[110:111], v[112:113], v[10:11], v[110:111] op_sel:[1,0,0]
	s_waitcnt lgkmcnt(0)
	v_pk_fma_f32 v[110:111], v[118:119], v[14:15], v[110:111] op_sel_hi:[0,1,1]
	v_pk_fma_f32 v[110:111], v[118:119], v[4:5], v[110:111] op_sel:[1,0,0]
	v_pk_fma_f32 v[110:111], v[120:121], v[0:1], v[110:111] op_sel_hi:[0,1,1]
	v_pk_fma_f32 v[110:111], v[120:121], v[2:3], v[110:111] op_sel:[1,0,0]
	v_pk_fma_f32 v[112:113], v[104:105], v[6:7], v[122:123] neg_lo:[0,0,1] neg_hi:[0,0,1]
	v_pk_fma_f32 v[6:7], v[104:105], v[6:7], v[122:123]
	s_nop 0
	v_mov_b32_e32 v113, v7
	v_pk_add_f32 v[6:7], v[112:113], v[110:111]
	ds_read_b128 v[110:113], v41 offset:128
	ds_read_b128 v[114:117], v41 offset:144
	v_pk_mul_f32 v[122:123], v[106:107], v[6:7] op_sel:[0,1] op_sel_hi:[1,0]
	s_waitcnt lgkmcnt(1)
	v_pk_fma_f32 v[118:119], v[110:111], v[108:109], 0 op_sel_hi:[0,1,0]
	v_pk_fma_f32 v[110:111], v[110:111], v[28:29], v[118:119] op_sel:[1,0,0]
	s_nop 0
	v_pk_fma_f32 v[110:111], v[112:113], v[24:25], v[110:111] op_sel_hi:[0,1,1]
	v_pk_fma_f32 v[110:111], v[112:113], v[26:27], v[110:111] op_sel:[1,0,0]
	s_waitcnt lgkmcnt(0)
	v_pk_fma_f32 v[110:111], v[114:115], v[30:31], v[110:111] op_sel_hi:[0,1,1]
	v_pk_fma_f32 v[114:115], v[114:115], v[20:21], v[110:111] op_sel:[1,0,0]
	ds_read_b128 v[110:113], v41 offset:160
	ds_read_b128 v[118:121], v41 offset:176
	v_pk_fma_f32 v[114:115], v[116:117], v[16:17], v[114:115] op_sel_hi:[0,1,1]
	v_pk_fma_f32 v[114:115], v[116:117], v[18:19], v[114:115] op_sel:[1,0,0]
	s_waitcnt lgkmcnt(1)
	v_pk_fma_f32 v[114:115], v[110:111], v[22:23], v[114:115] op_sel_hi:[0,1,1]
	v_pk_fma_f32 v[110:111], v[110:111], v[12:13], v[114:115] op_sel:[1,0,0]
	s_nop 0
	v_pk_fma_f32 v[110:111], v[112:113], v[8:9], v[110:111] op_sel_hi:[0,1,1]
	v_pk_fma_f32 v[110:111], v[112:113], v[10:11], v[110:111] op_sel:[1,0,0]
	s_waitcnt lgkmcnt(0)
	v_pk_fma_f32 v[110:111], v[118:119], v[14:15], v[110:111] op_sel_hi:[0,1,1]
	v_pk_fma_f32 v[110:111], v[118:119], v[4:5], v[110:111] op_sel:[1,0,0]
	v_pk_fma_f32 v[110:111], v[120:121], v[0:1], v[110:111] op_sel_hi:[0,1,1]
	v_pk_fma_f32 v[110:111], v[120:121], v[2:3], v[110:111] op_sel:[1,0,0]
	v_pk_fma_f32 v[112:113], v[104:105], v[6:7], v[122:123] neg_lo:[0,0,1] neg_hi:[0,0,1]
	v_pk_fma_f32 v[6:7], v[104:105], v[6:7], v[122:123]
	s_nop 0
	v_mov_b32_e32 v113, v7
	v_pk_add_f32 v[6:7], v[112:113], v[110:111]
	ds_read_b128 v[110:113], v41 offset:192
	ds_read_b128 v[114:117], v41 offset:208
	v_pk_mul_f32 v[122:123], v[106:107], v[6:7] op_sel:[0,1] op_sel_hi:[1,0]
	s_waitcnt lgkmcnt(1)
	v_pk_fma_f32 v[118:119], v[110:111], v[108:109], 0 op_sel_hi:[0,1,0]
	v_pk_fma_f32 v[110:111], v[110:111], v[28:29], v[118:119] op_sel:[1,0,0]
	s_nop 0
	v_pk_fma_f32 v[110:111], v[112:113], v[24:25], v[110:111] op_sel_hi:[0,1,1]
	v_pk_fma_f32 v[110:111], v[112:113], v[26:27], v[110:111] op_sel:[1,0,0]
	s_waitcnt lgkmcnt(0)
	v_pk_fma_f32 v[110:111], v[114:115], v[30:31], v[110:111] op_sel_hi:[0,1,1]
	v_pk_fma_f32 v[114:115], v[114:115], v[20:21], v[110:111] op_sel:[1,0,0]
	ds_read_b128 v[110:113], v41 offset:224
	ds_read_b128 v[118:121], v41 offset:240
	v_pk_fma_f32 v[114:115], v[116:117], v[16:17], v[114:115] op_sel_hi:[0,1,1]
	v_pk_fma_f32 v[114:115], v[116:117], v[18:19], v[114:115] op_sel:[1,0,0]
	s_waitcnt lgkmcnt(1)
	v_pk_fma_f32 v[114:115], v[110:111], v[22:23], v[114:115] op_sel_hi:[0,1,1]
	v_pk_fma_f32 v[110:111], v[110:111], v[12:13], v[114:115] op_sel:[1,0,0]
	s_nop 0
	v_pk_fma_f32 v[110:111], v[112:113], v[8:9], v[110:111] op_sel_hi:[0,1,1]
	v_pk_fma_f32 v[110:111], v[112:113], v[10:11], v[110:111] op_sel:[1,0,0]
	s_waitcnt lgkmcnt(0)
	v_pk_fma_f32 v[110:111], v[118:119], v[14:15], v[110:111] op_sel_hi:[0,1,1]
	v_pk_fma_f32 v[110:111], v[118:119], v[4:5], v[110:111] op_sel:[1,0,0]
	v_pk_fma_f32 v[110:111], v[120:121], v[0:1], v[110:111] op_sel_hi:[0,1,1]
	v_pk_fma_f32 v[110:111], v[120:121], v[2:3], v[110:111] op_sel:[1,0,0]
	v_pk_fma_f32 v[112:113], v[104:105], v[6:7], v[122:123] neg_lo:[0,0,1] neg_hi:[0,0,1]
	v_pk_fma_f32 v[6:7], v[104:105], v[6:7], v[122:123]
	s_nop 0
	v_mov_b32_e32 v113, v7
	v_pk_add_f32 v[6:7], v[112:113], v[110:111]
	ds_read_b128 v[110:113], v41 offset:256
	ds_read_b128 v[114:117], v41 offset:272
	v_pk_mul_f32 v[122:123], v[106:107], v[6:7] op_sel:[0,1] op_sel_hi:[1,0]
	s_waitcnt lgkmcnt(1)
	v_pk_fma_f32 v[118:119], v[110:111], v[108:109], 0 op_sel_hi:[0,1,0]
	v_pk_fma_f32 v[110:111], v[110:111], v[28:29], v[118:119] op_sel:[1,0,0]
	s_nop 0
	v_pk_fma_f32 v[110:111], v[112:113], v[24:25], v[110:111] op_sel_hi:[0,1,1]
	v_pk_fma_f32 v[110:111], v[112:113], v[26:27], v[110:111] op_sel:[1,0,0]
	s_waitcnt lgkmcnt(0)
	v_pk_fma_f32 v[110:111], v[114:115], v[30:31], v[110:111] op_sel_hi:[0,1,1]
	v_pk_fma_f32 v[114:115], v[114:115], v[20:21], v[110:111] op_sel:[1,0,0]
	ds_read_b128 v[110:113], v41 offset:288
	ds_read_b128 v[118:121], v41 offset:304
	v_pk_fma_f32 v[114:115], v[116:117], v[16:17], v[114:115] op_sel_hi:[0,1,1]
	v_pk_fma_f32 v[114:115], v[116:117], v[18:19], v[114:115] op_sel:[1,0,0]
	s_waitcnt lgkmcnt(1)
	v_pk_fma_f32 v[114:115], v[110:111], v[22:23], v[114:115] op_sel_hi:[0,1,1]
	v_pk_fma_f32 v[110:111], v[110:111], v[12:13], v[114:115] op_sel:[1,0,0]
	s_nop 0
	v_pk_fma_f32 v[110:111], v[112:113], v[8:9], v[110:111] op_sel_hi:[0,1,1]
	v_pk_fma_f32 v[110:111], v[112:113], v[10:11], v[110:111] op_sel:[1,0,0]
	s_waitcnt lgkmcnt(0)
	v_pk_fma_f32 v[110:111], v[118:119], v[14:15], v[110:111] op_sel_hi:[0,1,1]
	v_pk_fma_f32 v[110:111], v[118:119], v[4:5], v[110:111] op_sel:[1,0,0]
	v_pk_fma_f32 v[110:111], v[120:121], v[0:1], v[110:111] op_sel_hi:[0,1,1]
	v_pk_fma_f32 v[110:111], v[120:121], v[2:3], v[110:111] op_sel:[1,0,0]
	v_pk_fma_f32 v[112:113], v[104:105], v[6:7], v[122:123] neg_lo:[0,0,1] neg_hi:[0,0,1]
	v_pk_fma_f32 v[6:7], v[104:105], v[6:7], v[122:123]
	s_nop 0
	v_mov_b32_e32 v113, v7
	v_pk_add_f32 v[6:7], v[112:113], v[110:111]
	ds_read_b128 v[110:113], v41 offset:320
	ds_read_b128 v[114:117], v41 offset:336
	v_pk_mul_f32 v[122:123], v[106:107], v[6:7] op_sel:[0,1] op_sel_hi:[1,0]
	s_waitcnt lgkmcnt(1)
	v_pk_fma_f32 v[118:119], v[110:111], v[108:109], 0 op_sel_hi:[0,1,0]
	v_pk_fma_f32 v[110:111], v[110:111], v[28:29], v[118:119] op_sel:[1,0,0]
	s_nop 0
	v_pk_fma_f32 v[110:111], v[112:113], v[24:25], v[110:111] op_sel_hi:[0,1,1]
	v_pk_fma_f32 v[110:111], v[112:113], v[26:27], v[110:111] op_sel:[1,0,0]
	s_waitcnt lgkmcnt(0)
	v_pk_fma_f32 v[110:111], v[114:115], v[30:31], v[110:111] op_sel_hi:[0,1,1]
	v_pk_fma_f32 v[114:115], v[114:115], v[20:21], v[110:111] op_sel:[1,0,0]
	ds_read_b128 v[110:113], v41 offset:352
	ds_read_b128 v[118:121], v41 offset:368
	v_pk_fma_f32 v[114:115], v[116:117], v[16:17], v[114:115] op_sel_hi:[0,1,1]
	v_pk_fma_f32 v[114:115], v[116:117], v[18:19], v[114:115] op_sel:[1,0,0]
	s_waitcnt lgkmcnt(1)
	v_pk_fma_f32 v[114:115], v[110:111], v[22:23], v[114:115] op_sel_hi:[0,1,1]
	v_pk_fma_f32 v[110:111], v[110:111], v[12:13], v[114:115] op_sel:[1,0,0]
	s_nop 0
	v_pk_fma_f32 v[110:111], v[112:113], v[8:9], v[110:111] op_sel_hi:[0,1,1]
	v_pk_fma_f32 v[110:111], v[112:113], v[10:11], v[110:111] op_sel:[1,0,0]
	s_waitcnt lgkmcnt(0)
	v_pk_fma_f32 v[110:111], v[118:119], v[14:15], v[110:111] op_sel_hi:[0,1,1]
	v_pk_fma_f32 v[110:111], v[118:119], v[4:5], v[110:111] op_sel:[1,0,0]
	v_pk_fma_f32 v[110:111], v[120:121], v[0:1], v[110:111] op_sel_hi:[0,1,1]
	v_pk_fma_f32 v[110:111], v[120:121], v[2:3], v[110:111] op_sel:[1,0,0]
	v_pk_fma_f32 v[112:113], v[104:105], v[6:7], v[122:123] neg_lo:[0,0,1] neg_hi:[0,0,1]
	v_pk_fma_f32 v[6:7], v[104:105], v[6:7], v[122:123]
	s_nop 0
	v_mov_b32_e32 v113, v7
	v_pk_add_f32 v[6:7], v[112:113], v[110:111]
	ds_read_b128 v[110:113], v41 offset:384
	ds_read_b128 v[114:117], v41 offset:400
	v_pk_mul_f32 v[122:123], v[106:107], v[6:7] op_sel:[0,1] op_sel_hi:[1,0]
	s_waitcnt lgkmcnt(1)
	v_pk_fma_f32 v[118:119], v[110:111], v[108:109], 0 op_sel_hi:[0,1,0]
	v_pk_fma_f32 v[110:111], v[110:111], v[28:29], v[118:119] op_sel:[1,0,0]
	s_nop 0
	v_pk_fma_f32 v[110:111], v[112:113], v[24:25], v[110:111] op_sel_hi:[0,1,1]
	v_pk_fma_f32 v[110:111], v[112:113], v[26:27], v[110:111] op_sel:[1,0,0]
	s_waitcnt lgkmcnt(0)
	v_pk_fma_f32 v[110:111], v[114:115], v[30:31], v[110:111] op_sel_hi:[0,1,1]
	v_pk_fma_f32 v[114:115], v[114:115], v[20:21], v[110:111] op_sel:[1,0,0]
	ds_read_b128 v[110:113], v41 offset:416
	ds_read_b128 v[118:121], v41 offset:432
	v_pk_fma_f32 v[114:115], v[116:117], v[16:17], v[114:115] op_sel_hi:[0,1,1]
	v_pk_fma_f32 v[114:115], v[116:117], v[18:19], v[114:115] op_sel:[1,0,0]
	s_waitcnt lgkmcnt(1)
	v_pk_fma_f32 v[114:115], v[110:111], v[22:23], v[114:115] op_sel_hi:[0,1,1]
	v_pk_fma_f32 v[110:111], v[110:111], v[12:13], v[114:115] op_sel:[1,0,0]
	s_nop 0
	v_pk_fma_f32 v[110:111], v[112:113], v[8:9], v[110:111] op_sel_hi:[0,1,1]
	v_pk_fma_f32 v[110:111], v[112:113], v[10:11], v[110:111] op_sel:[1,0,0]
	s_waitcnt lgkmcnt(0)
	v_pk_fma_f32 v[110:111], v[118:119], v[14:15], v[110:111] op_sel_hi:[0,1,1]
	v_pk_fma_f32 v[110:111], v[118:119], v[4:5], v[110:111] op_sel:[1,0,0]
	v_pk_fma_f32 v[110:111], v[120:121], v[0:1], v[110:111] op_sel_hi:[0,1,1]
	v_pk_fma_f32 v[110:111], v[120:121], v[2:3], v[110:111] op_sel:[1,0,0]
	v_pk_fma_f32 v[112:113], v[104:105], v[6:7], v[122:123] neg_lo:[0,0,1] neg_hi:[0,0,1]
	v_pk_fma_f32 v[6:7], v[104:105], v[6:7], v[122:123]
	s_nop 0
	v_mov_b32_e32 v113, v7
	v_pk_add_f32 v[6:7], v[112:113], v[110:111]
	ds_read_b128 v[110:113], v41 offset:448
	ds_read_b128 v[114:117], v41 offset:464
	v_pk_mul_f32 v[122:123], v[106:107], v[6:7] op_sel:[0,1] op_sel_hi:[1,0]
	s_waitcnt lgkmcnt(1)
	v_pk_fma_f32 v[118:119], v[110:111], v[108:109], 0 op_sel_hi:[0,1,0]
	v_pk_fma_f32 v[110:111], v[110:111], v[28:29], v[118:119] op_sel:[1,0,0]
	s_nop 0
	v_pk_fma_f32 v[110:111], v[112:113], v[24:25], v[110:111] op_sel_hi:[0,1,1]
	v_pk_fma_f32 v[110:111], v[112:113], v[26:27], v[110:111] op_sel:[1,0,0]
	s_waitcnt lgkmcnt(0)
	v_pk_fma_f32 v[110:111], v[114:115], v[30:31], v[110:111] op_sel_hi:[0,1,1]
	v_pk_fma_f32 v[114:115], v[114:115], v[20:21], v[110:111] op_sel:[1,0,0]
	ds_read_b128 v[110:113], v41 offset:480
	ds_read_b128 v[118:121], v41 offset:496
	v_pk_fma_f32 v[114:115], v[116:117], v[16:17], v[114:115] op_sel_hi:[0,1,1]
	v_pk_fma_f32 v[114:115], v[116:117], v[18:19], v[114:115] op_sel:[1,0,0]
	s_waitcnt lgkmcnt(1)
	v_pk_fma_f32 v[114:115], v[110:111], v[22:23], v[114:115] op_sel_hi:[0,1,1]
	v_pk_fma_f32 v[110:111], v[110:111], v[12:13], v[114:115] op_sel:[1,0,0]
	s_nop 0
	v_pk_fma_f32 v[110:111], v[112:113], v[8:9], v[110:111] op_sel_hi:[0,1,1]
	v_pk_fma_f32 v[110:111], v[112:113], v[10:11], v[110:111] op_sel:[1,0,0]
	s_waitcnt lgkmcnt(0)
	v_pk_fma_f32 v[110:111], v[118:119], v[14:15], v[110:111] op_sel_hi:[0,1,1]
	v_pk_fma_f32 v[110:111], v[118:119], v[4:5], v[110:111] op_sel:[1,0,0]
	v_pk_fma_f32 v[110:111], v[120:121], v[0:1], v[110:111] op_sel_hi:[0,1,1]
	v_pk_fma_f32 v[110:111], v[120:121], v[2:3], v[110:111] op_sel:[1,0,0]
	v_pk_fma_f32 v[112:113], v[104:105], v[6:7], v[122:123] neg_lo:[0,0,1] neg_hi:[0,0,1]
	v_pk_fma_f32 v[6:7], v[104:105], v[6:7], v[122:123]
	s_nop 0
	v_mov_b32_e32 v113, v7
	v_pk_add_f32 v[6:7], v[112:113], v[110:111]
	s_cbranch_scc1 .LBB0_279
	s_waitcnt lgkmcnt(0)
	s_load_dwordx2 s[4:5], s[0:1], 0x150
	v_ashrrev_i32_e32 v103, 31, v102
	v_lshlrev_b64 v[0:1], 9, v[102:103]
	v_mov_b32_e32 v97, v169
	s_waitcnt lgkmcnt(0)
	v_lshl_add_u64 v[0:1], s[4:5], 0, v[0:1]
	v_lshl_add_u64 v[0:1], v[0:1], 0, v[96:97]
	v_add_co_u32_e32 v0, vcc, 0x2d381000, v0
	s_mov_b64 s[4:5], 0
	s_nop 0
	v_addc_co_u32_e32 v1, vcc, 0, v1, vcc
	global_store_dwordx2 v[0:1], v[6:7], off offset:2048

.LBB0_880:
	v_add_u32_e32 v43, s4, v110
	v_add_u32_e32 v252, 0x11800, v43
	ds_read_b128 v[130:133], v252
	ds_read_b128 v[134:137], v252 offset:16
	v_pk_mul_f32 v[142:143], v[52:53], v[66:67]
	s_waitcnt lgkmcnt(0)
	v_pk_fma_f32 v[138:139], v[130:131], v[54:55], 0 op_sel_hi:[0,1,0]
	v_pk_fma_f32 v[130:131], v[130:131], v[56:57], v[138:139] op_sel:[1,0,0]
	s_addk_i32 s4, 0x200
	v_pk_fma_f32 v[130:131], v[132:133], v[58:59], v[130:131] op_sel_hi:[0,1,1]
	v_pk_fma_f32 v[130:131], v[132:133], v[60:61], v[130:131] op_sel:[1,0,0]
	v_pk_fma_f32 v[130:131], v[134:135], v[62:63], v[130:131] op_sel_hi:[0,1,1]
	v_pk_fma_f32 v[134:135], v[134:135], v[64:65], v[130:131] op_sel:[1,0,0]
	ds_read_b128 v[130:133], v252 offset:32
	v_pk_fma_f32 v[134:135], v[136:137], v[68:69], v[134:135] op_sel_hi:[0,1,1]
	ds_read_b128 v[138:141], v252 offset:48
	v_pk_fma_f32 v[134:135], v[136:137], v[70:71], v[134:135] op_sel:[1,0,0]
	s_waitcnt lgkmcnt(1)
	v_pk_fma_f32 v[134:135], v[130:131], v[72:73], v[134:135] op_sel_hi:[0,1,1]
	v_pk_fma_f32 v[130:131], v[130:131], v[74:75], v[134:135] op_sel:[1,0,0]
	s_cmp_eq_u32 s4, 0
	v_pk_fma_f32 v[130:131], v[132:133], v[76:77], v[130:131] op_sel_hi:[0,1,1]
	v_pk_fma_f32 v[130:131], v[132:133], v[78:79], v[130:131] op_sel:[1,0,0]
	s_waitcnt lgkmcnt(0)
	v_pk_fma_f32 v[130:131], v[138:139], v[80:81], v[130:131] op_sel_hi:[0,1,1]
	v_pk_fma_f32 v[130:131], v[138:139], v[82:83], v[130:131] op_sel:[1,0,0]
	v_pk_fma_f32 v[130:131], v[140:141], v[84:85], v[130:131] op_sel_hi:[0,1,1]
	v_pk_fma_f32 v[130:131], v[140:141], v[86:87], v[130:131] op_sel:[1,0,0]
	v_pk_fma_f32 v[132:133], v[88:89], v[66:67], v[142:143] op_sel:[0,0,1] op_sel_hi:[1,1,0]
	v_pk_fma_f32 v[66:67], v[88:89], v[66:67], v[142:143] op_sel:[0,0,1] op_sel_hi:[1,1,0] neg_lo:[0,0,1] neg_hi:[0,0,1]
	s_nop 0
	v_mov_b32_e32 v133, v67
	v_pk_add_f32 v[66:67], v[132:133], v[130:131]
	s_nop 0
	v_cvt_pk_bf16_f32 v45, v66, v67
	ds_write_b16_d16_hi v41, v45
	ds_write_b16 v41, v45 offset:128
	ds_read_b128 v[130:133], v252 offset:64
	ds_read_b128 v[134:137], v252 offset:80
	v_pk_mul_f32 v[142:143], v[52:53], v[66:67]
	s_waitcnt lgkmcnt(1)
	v_pk_fma_f32 v[138:139], v[130:131], v[54:55], 0 op_sel_hi:[0,1,0]
	v_pk_fma_f32 v[130:131], v[130:131], v[56:57], v[138:139] op_sel:[1,0,0]
	s_nop 0
	v_pk_fma_f32 v[130:131], v[132:133], v[58:59], v[130:131] op_sel_hi:[0,1,1]
	v_pk_fma_f32 v[130:131], v[132:133], v[60:61], v[130:131] op_sel:[1,0,0]
	s_waitcnt lgkmcnt(0)
	v_pk_fma_f32 v[130:131], v[134:135], v[62:63], v[130:131] op_sel_hi:[0,1,1]
	v_pk_fma_f32 v[134:135], v[134:135], v[64:65], v[130:131] op_sel:[1,0,0]
	ds_read_b128 v[130:133], v252 offset:96
	v_pk_fma_f32 v[134:135], v[136:137], v[68:69], v[134:135] op_sel_hi:[0,1,1]
	ds_read_b128 v[138:141], v252 offset:112
	v_pk_fma_f32 v[134:135], v[136:137], v[70:71], v[134:135] op_sel:[1,0,0]
	s_waitcnt lgkmcnt(1)
	v_pk_fma_f32 v[134:135], v[130:131], v[72:73], v[134:135] op_sel_hi:[0,1,1]
	v_pk_fma_f32 v[130:131], v[130:131], v[74:75], v[134:135] op_sel:[1,0,0]
	s_nop 0
	v_pk_fma_f32 v[130:131], v[132:133], v[76:77], v[130:131] op_sel_hi:[0,1,1]
	v_pk_fma_f32 v[130:131], v[132:133], v[78:79], v[130:131] op_sel:[1,0,0]
	s_waitcnt lgkmcnt(0)
	v_pk_fma_f32 v[130:131], v[138:139], v[80:81], v[130:131] op_sel_hi:[0,1,1]
	v_pk_fma_f32 v[130:131], v[138:139], v[82:83], v[130:131] op_sel:[1,0,0]
	v_pk_fma_f32 v[130:131], v[140:141], v[84:85], v[130:131] op_sel_hi:[0,1,1]
	v_pk_fma_f32 v[130:131], v[140:141], v[86:87], v[130:131] op_sel:[1,0,0]
	v_pk_fma_f32 v[132:133], v[88:89], v[66:67], v[142:143] op_sel:[0,0,1] op_sel_hi:[1,1,0]
	v_pk_fma_f32 v[66:67], v[88:89], v[66:67], v[142:143] op_sel:[0,0,1] op_sel_hi:[1,1,0] neg_lo:[0,0,1] neg_hi:[0,0,1]
	s_nop 0
	v_mov_b32_e32 v133, v67
	v_pk_add_f32 v[66:67], v[132:133], v[130:131]
	s_nop 0
	v_cvt_pk_bf16_f32 v45, v66, v67
	ds_write_b16_d16_hi v41, v45 offset:272
	ds_write_b16 v41, v45 offset:400
	ds_read_b128 v[130:133], v252 offset:128
	ds_read_b128 v[134:137], v252 offset:144
	v_pk_mul_f32 v[142:143], v[52:53], v[66:67]
	s_waitcnt lgkmcnt(1)
	v_pk_fma_f32 v[138:139], v[130:131], v[54:55], 0 op_sel_hi:[0,1,0]
	v_pk_fma_f32 v[130:131], v[130:131], v[56:57], v[138:139] op_sel:[1,0,0]
	s_nop 0
	v_pk_fma_f32 v[130:131], v[132:133], v[58:59], v[130:131] op_sel_hi:[0,1,1]
	v_pk_fma_f32 v[130:131], v[132:133], v[60:61], v[130:131] op_sel:[1,0,0]
	s_waitcnt lgkmcnt(0)
	v_pk_fma_f32 v[130:131], v[134:135], v[62:63], v[130:131] op_sel_hi:[0,1,1]
	v_pk_fma_f32 v[134:135], v[134:135], v[64:65], v[130:131] op_sel:[1,0,0]
	ds_read_b128 v[130:133], v252 offset:160
	v_pk_fma_f32 v[134:135], v[136:137], v[68:69], v[134:135] op_sel_hi:[0,1,1]
	ds_read_b128 v[138:141], v252 offset:176
	v_pk_fma_f32 v[134:135], v[136:137], v[70:71], v[134:135] op_sel:[1,0,0]
	s_waitcnt lgkmcnt(1)
	v_pk_fma_f32 v[134:135], v[130:131], v[72:73], v[134:135] op_sel_hi:[0,1,1]
	v_pk_fma_f32 v[130:131], v[130:131], v[74:75], v[134:135] op_sel:[1,0,0]
	s_nop 0
	v_pk_fma_f32 v[130:131], v[132:133], v[76:77], v[130:131] op_sel_hi:[0,1,1]
	v_pk_fma_f32 v[130:131], v[132:133], v[78:79], v[130:131] op_sel:[1,0,0]
	s_waitcnt lgkmcnt(0)
	v_pk_fma_f32 v[130:131], v[138:139], v[80:81], v[130:131] op_sel_hi:[0,1,1]
	v_pk_fma_f32 v[130:131], v[138:139], v[82:83], v[130:131] op_sel:[1,0,0]
	v_pk_fma_f32 v[130:131], v[140:141], v[84:85], v[130:131] op_sel_hi:[0,1,1]
	v_pk_fma_f32 v[130:131], v[140:141], v[86:87], v[130:131] op_sel:[1,0,0]
	v_pk_fma_f32 v[132:133], v[88:89], v[66:67], v[142:143] op_sel:[0,0,1] op_sel_hi:[1,1,0]
	v_pk_fma_f32 v[66:67], v[88:89], v[66:67], v[142:143] op_sel:[0,0,1] op_sel_hi:[1,1,0] neg_lo:[0,0,1] neg_hi:[0,0,1]
	s_nop 0
	v_mov_b32_e32 v133, v67
	v_pk_add_f32 v[66:67], v[132:133], v[130:131]
	s_nop 0
	v_cvt_pk_bf16_f32 v45, v66, v67
	ds_write_b16_d16_hi v41, v45 offset:544
	ds_write_b16 v41, v45 offset:672
	ds_read_b128 v[130:133], v252 offset:192
	ds_read_b128 v[134:137], v252 offset:208
	v_pk_mul_f32 v[142:143], v[52:53], v[66:67]
	s_waitcnt lgkmcnt(1)
	v_pk_fma_f32 v[138:139], v[130:131], v[54:55], 0 op_sel_hi:[0,1,0]
	v_pk_fma_f32 v[130:131], v[130:131], v[56:57], v[138:139] op_sel:[1,0,0]
	s_nop 0
	v_pk_fma_f32 v[130:131], v[132:133], v[58:59], v[130:131] op_sel_hi:[0,1,1]
	v_pk_fma_f32 v[130:131], v[132:133], v[60:61], v[130:131] op_sel:[1,0,0]
	s_waitcnt lgkmcnt(0)
	v_pk_fma_f32 v[130:131], v[134:135], v[62:63], v[130:131] op_sel_hi:[0,1,1]
	v_pk_fma_f32 v[134:135], v[134:135], v[64:65], v[130:131] op_sel:[1,0,0]
	ds_read_b128 v[130:133], v252 offset:224
	v_pk_fma_f32 v[134:135], v[136:137], v[68:69], v[134:135] op_sel_hi:[0,1,1]
	ds_read_b128 v[138:141], v252 offset:240
	v_pk_fma_f32 v[134:135], v[136:137], v[70:71], v[134:135] op_sel:[1,0,0]
	s_waitcnt lgkmcnt(1)
	v_pk_fma_f32 v[134:135], v[130:131], v[72:73], v[134:135] op_sel_hi:[0,1,1]
	v_pk_fma_f32 v[130:131], v[130:131], v[74:75], v[134:135] op_sel:[1,0,0]
	s_nop 0
	v_pk_fma_f32 v[130:131], v[132:133], v[76:77], v[130:131] op_sel_hi:[0,1,1]
	v_pk_fma_f32 v[130:131], v[132:133], v[78:79], v[130:131] op_sel:[1,0,0]
	s_waitcnt lgkmcnt(0)
	v_pk_fma_f32 v[130:131], v[138:139], v[80:81], v[130:131] op_sel_hi:[0,1,1]
	v_pk_fma_f32 v[130:131], v[138:139], v[82:83], v[130:131] op_sel:[1,0,0]
	v_pk_fma_f32 v[130:131], v[140:141], v[84:85], v[130:131] op_sel_hi:[0,1,1]
	v_pk_fma_f32 v[130:131], v[140:141], v[86:87], v[130:131] op_sel:[1,0,0]
	v_pk_fma_f32 v[132:133], v[88:89], v[66:67], v[142:143] op_sel:[0,0,1] op_sel_hi:[1,1,0]
	v_pk_fma_f32 v[66:67], v[88:89], v[66:67], v[142:143] op_sel:[0,0,1] op_sel_hi:[1,1,0] neg_lo:[0,0,1] neg_hi:[0,0,1]
	s_nop 0
	v_mov_b32_e32 v133, v67
	v_pk_add_f32 v[66:67], v[132:133], v[130:131]
	s_nop 0
	v_cvt_pk_bf16_f32 v45, v66, v67
	ds_write_b16_d16_hi v41, v45 offset:816
	ds_write_b16 v41, v45 offset:944
	ds_read_b128 v[130:133], v252 offset:256
	ds_read_b128 v[134:137], v252 offset:272
	v_pk_mul_f32 v[142:143], v[52:53], v[66:67]
	s_waitcnt lgkmcnt(1)
	v_pk_fma_f32 v[138:139], v[130:131], v[54:55], 0 op_sel_hi:[0,1,0]
	v_pk_fma_f32 v[130:131], v[130:131], v[56:57], v[138:139] op_sel:[1,0,0]
	s_nop 0
	v_pk_fma_f32 v[130:131], v[132:133], v[58:59], v[130:131] op_sel_hi:[0,1,1]
	v_pk_fma_f32 v[130:131], v[132:133], v[60:61], v[130:131] op_sel:[1,0,0]
	s_waitcnt lgkmcnt(0)
	v_pk_fma_f32 v[130:131], v[134:135], v[62:63], v[130:131] op_sel_hi:[0,1,1]
	v_pk_fma_f32 v[134:135], v[134:135], v[64:65], v[130:131] op_sel:[1,0,0]
	ds_read_b128 v[130:133], v252 offset:288
	v_pk_fma_f32 v[134:135], v[136:137], v[68:69], v[134:135] op_sel_hi:[0,1,1]
	ds_read_b128 v[138:141], v252 offset:304
	v_pk_fma_f32 v[134:135], v[136:137], v[70:71], v[134:135] op_sel:[1,0,0]
	s_waitcnt lgkmcnt(1)
	v_pk_fma_f32 v[134:135], v[130:131], v[72:73], v[134:135] op_sel_hi:[0,1,1]
	v_pk_fma_f32 v[130:131], v[130:131], v[74:75], v[134:135] op_sel:[1,0,0]
	s_nop 0
	v_pk_fma_f32 v[130:131], v[132:133], v[76:77], v[130:131] op_sel_hi:[0,1,1]
	v_pk_fma_f32 v[130:131], v[132:133], v[78:79], v[130:131] op_sel:[1,0,0]
	s_waitcnt lgkmcnt(0)
	v_pk_fma_f32 v[130:131], v[138:139], v[80:81], v[130:131] op_sel_hi:[0,1,1]
	v_pk_fma_f32 v[130:131], v[138:139], v[82:83], v[130:131] op_sel:[1,0,0]
	v_pk_fma_f32 v[130:131], v[140:141], v[84:85], v[130:131] op_sel_hi:[0,1,1]
	v_pk_fma_f32 v[130:131], v[140:141], v[86:87], v[130:131] op_sel:[1,0,0]
	v_pk_fma_f32 v[132:133], v[88:89], v[66:67], v[142:143] op_sel:[0,0,1] op_sel_hi:[1,1,0]
	v_pk_fma_f32 v[66:67], v[88:89], v[66:67], v[142:143] op_sel:[0,0,1] op_sel_hi:[1,1,0] neg_lo:[0,0,1] neg_hi:[0,0,1]
	s_nop 0
	v_mov_b32_e32 v133, v67
	v_pk_add_f32 v[66:67], v[132:133], v[130:131]
	s_nop 0
	v_cvt_pk_bf16_f32 v45, v66, v67
	ds_write_b16_d16_hi v41, v45 offset:1088
	ds_write_b16 v41, v45 offset:1216
	ds_read_b128 v[130:133], v252 offset:320
	ds_read_b128 v[134:137], v252 offset:336
	v_pk_mul_f32 v[142:143], v[52:53], v[66:67]
	s_waitcnt lgkmcnt(1)
	v_pk_fma_f32 v[138:139], v[130:131], v[54:55], 0 op_sel_hi:[0,1,0]
	v_pk_fma_f32 v[130:131], v[130:131], v[56:57], v[138:139] op_sel:[1,0,0]
	s_nop 0
	v_pk_fma_f32 v[130:131], v[132:133], v[58:59], v[130:131] op_sel_hi:[0,1,1]
	v_pk_fma_f32 v[130:131], v[132:133], v[60:61], v[130:131] op_sel:[1,0,0]
	s_waitcnt lgkmcnt(0)
	v_pk_fma_f32 v[130:131], v[134:135], v[62:63], v[130:131] op_sel_hi:[0,1,1]
	v_pk_fma_f32 v[134:135], v[134:135], v[64:65], v[130:131] op_sel:[1,0,0]
	ds_read_b128 v[130:133], v252 offset:352
	v_pk_fma_f32 v[134:135], v[136:137], v[68:69], v[134:135] op_sel_hi:[0,1,1]
	ds_read_b128 v[138:141], v252 offset:368
	v_pk_fma_f32 v[134:135], v[136:137], v[70:71], v[134:135] op_sel:[1,0,0]
	s_waitcnt lgkmcnt(1)
	v_pk_fma_f32 v[134:135], v[130:131], v[72:73], v[134:135] op_sel_hi:[0,1,1]
	v_pk_fma_f32 v[130:131], v[130:131], v[74:75], v[134:135] op_sel:[1,0,0]
	s_nop 0
	v_pk_fma_f32 v[130:131], v[132:133], v[76:77], v[130:131] op_sel_hi:[0,1,1]
	v_pk_fma_f32 v[130:131], v[132:133], v[78:79], v[130:131] op_sel:[1,0,0]
	s_waitcnt lgkmcnt(0)
	v_pk_fma_f32 v[130:131], v[138:139], v[80:81], v[130:131] op_sel_hi:[0,1,1]
	v_pk_fma_f32 v[130:131], v[138:139], v[82:83], v[130:131] op_sel:[1,0,0]
	v_pk_fma_f32 v[130:131], v[140:141], v[84:85], v[130:131] op_sel_hi:[0,1,1]
	v_pk_fma_f32 v[130:131], v[140:141], v[86:87], v[130:131] op_sel:[1,0,0]
	v_pk_fma_f32 v[132:133], v[88:89], v[66:67], v[142:143] op_sel:[0,0,1] op_sel_hi:[1,1,0]
	v_pk_fma_f32 v[66:67], v[88:89], v[66:67], v[142:143] op_sel:[0,0,1] op_sel_hi:[1,1,0] neg_lo:[0,0,1] neg_hi:[0,0,1]
	s_nop 0
	v_mov_b32_e32 v133, v67
	v_pk_add_f32 v[66:67], v[132:133], v[130:131]
	s_nop 0
	v_cvt_pk_bf16_f32 v45, v66, v67
	ds_write_b16_d16_hi v41, v45 offset:1360
	ds_write_b16 v41, v45 offset:1488
	ds_read_b128 v[130:133], v252 offset:384
	ds_read_b128 v[134:137], v252 offset:400
	v_pk_mul_f32 v[142:143], v[52:53], v[66:67]
	s_waitcnt lgkmcnt(1)
	v_pk_fma_f32 v[138:139], v[130:131], v[54:55], 0 op_sel_hi:[0,1,0]
	v_pk_fma_f32 v[130:131], v[130:131], v[56:57], v[138:139] op_sel:[1,0,0]
	s_nop 0
	v_pk_fma_f32 v[130:131], v[132:133], v[58:59], v[130:131] op_sel_hi:[0,1,1]
	v_pk_fma_f32 v[130:131], v[132:133], v[60:61], v[130:131] op_sel:[1,0,0]
	s_waitcnt lgkmcnt(0)
	v_pk_fma_f32 v[130:131], v[134:135], v[62:63], v[130:131] op_sel_hi:[0,1,1]
	v_pk_fma_f32 v[134:135], v[134:135], v[64:65], v[130:131] op_sel:[1,0,0]
	ds_read_b128 v[130:133], v252 offset:416
	v_pk_fma_f32 v[134:135], v[136:137], v[68:69], v[134:135] op_sel_hi:[0,1,1]
	ds_read_b128 v[138:141], v252 offset:432
	v_pk_fma_f32 v[134:135], v[136:137], v[70:71], v[134:135] op_sel:[1,0,0]
	s_waitcnt lgkmcnt(1)
	v_pk_fma_f32 v[134:135], v[130:131], v[72:73], v[134:135] op_sel_hi:[0,1,1]
	v_pk_fma_f32 v[130:131], v[130:131], v[74:75], v[134:135] op_sel:[1,0,0]
	s_nop 0
	v_pk_fma_f32 v[130:131], v[132:133], v[76:77], v[130:131] op_sel_hi:[0,1,1]
	v_pk_fma_f32 v[130:131], v[132:133], v[78:79], v[130:131] op_sel:[1,0,0]
	s_waitcnt lgkmcnt(0)
	v_pk_fma_f32 v[130:131], v[138:139], v[80:81], v[130:131] op_sel_hi:[0,1,1]
	v_pk_fma_f32 v[130:131], v[138:139], v[82:83], v[130:131] op_sel:[1,0,0]
	v_pk_fma_f32 v[130:131], v[140:141], v[84:85], v[130:131] op_sel_hi:[0,1,1]
	v_pk_fma_f32 v[130:131], v[140:141], v[86:87], v[130:131] op_sel:[1,0,0]
	v_pk_fma_f32 v[132:133], v[88:89], v[66:67], v[142:143] op_sel:[0,0,1] op_sel_hi:[1,1,0]
	v_pk_fma_f32 v[66:67], v[88:89], v[66:67], v[142:143] op_sel:[0,0,1] op_sel_hi:[1,1,0] neg_lo:[0,0,1] neg_hi:[0,0,1]
	s_nop 0
	v_mov_b32_e32 v133, v67
	v_pk_add_f32 v[66:67], v[132:133], v[130:131]
	s_nop 0
	v_cvt_pk_bf16_f32 v45, v66, v67
	ds_write_b16_d16_hi v41, v45 offset:1632
	ds_write_b16 v41, v45 offset:1760
	ds_read_b128 v[130:133], v252 offset:448
	ds_read_b128 v[134:137], v252 offset:464
	s_waitcnt lgkmcnt(1)
	v_pk_fma_f32 v[138:139], v[130:131], v[54:55], 0 op_sel_hi:[0,1,0]
	v_pk_fma_f32 v[130:131], v[130:131], v[56:57], v[138:139] op_sel:[1,0,0]
	ds_read_b128 v[138:141], v252 offset:496
	v_pk_fma_f32 v[130:131], v[132:133], v[58:59], v[130:131] op_sel_hi:[0,1,1]
	v_pk_fma_f32 v[130:131], v[132:133], v[60:61], v[130:131] op_sel:[1,0,0]
	s_waitcnt lgkmcnt(1)
	v_pk_fma_f32 v[130:131], v[134:135], v[62:63], v[130:131] op_sel_hi:[0,1,1]
	v_pk_fma_f32 v[134:135], v[134:135], v[64:65], v[130:131] op_sel:[1,0,0]
	ds_read_b128 v[130:133], v252 offset:480
	v_pk_fma_f32 v[134:135], v[136:137], v[68:69], v[134:135] op_sel_hi:[0,1,1]
	v_pk_fma_f32 v[134:135], v[136:137], v[70:71], v[134:135] op_sel:[1,0,0]
	v_pk_mul_f32 v[142:143], v[52:53], v[66:67]
	s_waitcnt lgkmcnt(0)
	v_pk_fma_f32 v[134:135], v[130:131], v[72:73], v[134:135] op_sel_hi:[0,1,1]
	v_pk_fma_f32 v[130:131], v[130:131], v[74:75], v[134:135] op_sel:[1,0,0]
	s_nop 0
	v_pk_fma_f32 v[130:131], v[132:133], v[76:77], v[130:131] op_sel_hi:[0,1,1]
	v_pk_fma_f32 v[130:131], v[132:133], v[78:79], v[130:131] op_sel:[1,0,0]
	v_pk_fma_f32 v[130:131], v[138:139], v[80:81], v[130:131] op_sel_hi:[0,1,1]
	v_pk_fma_f32 v[130:131], v[138:139], v[82:83], v[130:131] op_sel:[1,0,0]
	v_pk_fma_f32 v[130:131], v[140:141], v[84:85], v[130:131] op_sel_hi:[0,1,1]
	v_pk_fma_f32 v[130:131], v[140:141], v[86:87], v[130:131] op_sel:[1,0,0]
	v_pk_fma_f32 v[132:133], v[88:89], v[66:67], v[142:143] op_sel:[0,0,1] op_sel_hi:[1,1,0]
	v_pk_fma_f32 v[66:67], v[88:89], v[66:67], v[142:143] op_sel:[0,0,1] op_sel_hi:[1,1,0] neg_lo:[0,0,1] neg_hi:[0,0,1]
	s_nop 0
	v_mov_b32_e32 v133, v67
	v_pk_add_f32 v[66:67], v[132:133], v[130:131]
	s_nop 0
	v_cvt_pk_bf16_f32 v43, v66, v67
	ds_write_b16_d16_hi v41, v43 offset:1904
	ds_write_b16 v41, v43 offset:2032
	v_add_u32_e32 v41, 0x880, v41
	s_cbranch_scc0 .LBB0_880
	s_waitcnt vmcnt(11)
	v_bfe_u32 v49, v7, 16, 1
	v_bfe_u32 v129, v6, 16, 1
	v_bfe_u32 v130, v5, 16, 1
	v_bfe_u32 v131, v4, 16, 1
	s_waitcnt vmcnt(5)
	v_pk_add_f32 v[8:9], v[8:9], 0 neg_lo:[1,1] neg_hi:[1,1]
	v_pk_add_f32 v[10:11], v[10:11], 0 neg_lo:[1,1] neg_hi:[1,1]
	v_add3_u32 v131, v4, v131, s43
	v_add3_u32 v130, v5, v130, s43
	v_add3_u32 v129, v6, v129, s43
	v_add3_u32 v49, v7, v49, s43
	v_bfe_u32 v4, v18, 16, 1
	v_bfe_u32 v5, v39, 16, 1
	v_bfe_u32 v6, v17, 16, 1
	v_bfe_u32 v7, v16, 16, 1
	s_waitcnt vmcnt(2)
	v_pk_add_f32 v[12:13], v[12:13], 0 neg_lo:[1,1] neg_hi:[1,1]
	v_pk_add_f32 v[14:15], v[14:15], 0 neg_lo:[1,1] neg_hi:[1,1]
	v_add3_u32 v16, v16, v7, s43
	v_add3_u32 v17, v17, v6, s43
	v_add3_u32 v39, v39, v5, s43
	v_add3_u32 v18, v18, v4, s43
	v_bfe_u32 v4, v11, 16, 1
	v_bfe_u32 v5, v10, 16, 1
	v_bfe_u32 v6, v9, 16, 1
	v_bfe_u32 v7, v8, 16, 1
	v_add3_u32 v135, v8, v7, s43
	v_add3_u32 v136, v9, v6, s43
	v_add3_u32 v137, v10, v5, s43
	v_add3_u32 v138, v11, v4, s43
	v_bfe_u32 v4, v15, 16, 1
	v_bfe_u32 v5, v14, 16, 1
	v_bfe_u32 v6, v13, 16, 1
	v_bfe_u32 v7, v12, 16, 1
	v_add3_u32 v139, v12, v7, s43
	v_add3_u32 v140, v13, v6, s43
	v_add3_u32 v141, v14, v5, s43
	v_add3_u32 v142, v15, v4, s43
	s_waitcnt lgkmcnt(0)
	ds_read_b128 v[4:7], v128
	ds_read_b128 v[12:15], v128 offset:64
	v_bfe_u32 v41, v22, 16, 1
	v_bfe_u32 v43, v19, 16, 1
	v_pk_add_f32 v[26:27], v[26:27], 0 neg_lo:[1,1] neg_hi:[1,1]
	v_bfe_u32 v45, v21, 16, 1
	v_bfe_u32 v47, v20, 16, 1
	v_add3_u32 v19, v19, v43, s43
	v_add3_u32 v41, v22, v41, s43
	v_bfe_u32 v22, v1, 16, 1
	v_bfe_u32 v43, v0, 16, 1
	v_pk_add_f32 v[24:25], v[24:25], 0 neg_lo:[1,1] neg_hi:[1,1]
	s_waitcnt vmcnt(1)
	v_pk_add_f32 v[30:31], v[30:31], 0 neg_lo:[1,1] neg_hi:[1,1]
	v_add3_u32 v47, v20, v47, s43
	v_add3_u32 v45, v21, v45, s43
	v_bfe_u32 v20, v3, 16, 1
	v_bfe_u32 v21, v2, 16, 1
	v_add3_u32 v43, v0, v43, s43
	v_add3_u32 v132, v1, v22, s43
	v_bfe_u32 v0, v27, 16, 1
	v_bfe_u32 v1, v26, 16, 1
	v_pk_add_f32 v[28:29], v[28:29], 0 neg_lo:[1,1] neg_hi:[1,1]
	v_lshl_add_u64 v[90:91], v[90:91], 1, s[6:7]
	v_add3_u32 v133, v2, v21, s43
	v_add3_u32 v134, v3, v20, s43
	v_bfe_u32 v2, v25, 16, 1
	v_bfe_u32 v3, v24, 16, 1
	v_add3_u32 v26, v26, v1, s43
	v_add3_u32 v27, v27, v0, s43
	v_bfe_u32 v0, v31, 16, 1
	v_bfe_u32 v1, v30, 16, 1
	v_lshlrev_b32_e32 v22, 15, v51
	v_mov_b32_e32 v51, v169
	v_add3_u32 v24, v24, v3, s43
	v_add3_u32 v25, v25, v2, s43
	v_bfe_u32 v2, v29, 16, 1
	v_bfe_u32 v3, v28, 16, 1
	v_add3_u32 v30, v30, v1, s43
	v_add3_u32 v31, v31, v0, s43
	v_lshl_add_u64 v[0:1], v[90:91], 0, v[50:51]
	s_mov_b64 s[4:5], 0x2d581800
	s_mov_b32 s2, 0x7060302
	v_add3_u32 v28, v28, v3, s43
	v_add3_u32 v29, v29, v2, s43
	v_lshl_add_u64 v[20:21], v[0:1], 0, s[4:5]
	v_perm_b32 v3, v19, v41, s2
	v_perm_b32 v2, v45, v47, s2
	v_perm_b32 v1, v49, v129, s2
	v_perm_b32 v0, v130, v131, s2
	s_movk_i32 s4, 0xf800
	s_waitcnt lgkmcnt(1)
	v_mfma_f32_16x16x32_bf16 v[8:11], v[4:7], v[0:3], 0
	v_perm_b32 v7, v39, v18, s2
	v_perm_b32 v6, v17, v16, s2
	ds_read_b128 v[16:19], v128 offset:128
	v_perm_b32 v5, v134, v133, s2
	v_perm_b32 v4, v132, v43, s2
	s_waitcnt lgkmcnt(1)
	s_nop 0
	v_mfma_f32_16x16x32_bf16 v[12:15], v[12:15], v[4:7], v[8:11]
	s_nop 2
	v_perm_b32 v11, v27, v26, s2
	v_perm_b32 v10, v25, v24, s2
	ds_read_b128 v[24:27], v128 offset:192
	v_perm_b32 v9, v138, v137, s2
	v_perm_b32 v8, v136, v135, s2
	s_waitcnt lgkmcnt(1)
	s_nop 0
	v_mfma_f32_16x16x32_bf16 v[16:19], v[16:19], v[8:11], v[12:15]
	s_nop 2
	v_perm_b32 v15, v31, v30, s2
	v_perm_b32 v14, v29, v28, s2
	v_perm_b32 v13, v142, v141, s2
	v_perm_b32 v12, v140, v139, s2
	s_waitcnt lgkmcnt(0)
	s_nop 0
	v_mfma_f32_16x16x32_bf16 v[16:19], v[24:27], v[12:15], v[16:19]
	ds_read_b32 v24, v112
	s_waitcnt vmcnt(0) lgkmcnt(0)
	s_nop 5
	v_fma_f32 v16, v23, v24, v16
	v_mul_f32_e32 v24, 0x3d372713, v16
	v_mul_f32_e32 v24, v16, v24
	v_fma_f32 v24, v16, v24, v16
	v_mul_f32_e32 v24, 0x3f4c422a, v24
	v_add_f32_e32 v24, v24, v24
	v_mul_f32_e32 v24, 0x3fb8aa3b, v24
	v_exp_f32_e32 v24, v24
	v_mul_f32_e32 v16, 0.5, v16
	v_add_f32_e32 v24, 1.0, v24
	v_rcp_f32_e32 v24, v24
	s_nop 0
	v_fma_f32 v24, v24, -2.0, 1.0
	v_add_f32_e32 v24, 1.0, v24
	v_mul_f32_e32 v16, v16, v24
	v_bfe_u32 v24, v16, 16, 1
	v_add3_u32 v16, v16, v24, s43
	v_or_b32_e32 v24, v22, v93
	v_lshlrev_b32_e32 v168, 1, v24
	v_lshl_add_u64 v[24:25], v[20:21], 0, v[168:169]
	global_store_short_d16_hi v[24:25], v16, off
	ds_read_b32 v16, v113
	s_waitcnt lgkmcnt(0)
	v_fma_f32 v16, v23, v16, v17
	v_mul_f32_e32 v17, 0x3d372713, v16
	v_mul_f32_e32 v17, v16, v17
	v_fma_f32 v17, v16, v17, v16
	v_mul_f32_e32 v17, 0x3f4c422a, v17
	v_add_f32_e32 v17, v17, v17
	v_mul_f32_e32 v17, 0x3fb8aa3b, v17
	v_exp_f32_e32 v17, v17
	v_mul_f32_e32 v16, 0.5, v16
	v_add_f32_e32 v17, 1.0, v17
	v_rcp_f32_e32 v17, v17
	s_nop 0
	v_fma_f32 v17, v17, -2.0, 1.0
	v_add_f32_e32 v17, 1.0, v17
	v_mul_f32_e32 v16, v16, v17
	v_bfe_u32 v17, v16, 16, 1
	v_add3_u32 v24, v16, v17, s43
	v_or_b32_e32 v16, v22, v94
	v_lshlrev_b32_e32 v168, 1, v16
	v_lshl_add_u64 v[16:17], v[20:21], 0, v[168:169]
	global_store_short_d16_hi v[16:17], v24, off
	ds_read_b32 v16, v114
	ds_read_b128 v[24:27], v128 offset:4416
	s_waitcnt lgkmcnt(1)
	v_fma_f32 v16, v23, v16, v18
	v_mul_f32_e32 v17, 0x3d372713, v16
	v_mul_f32_e32 v17, v16, v17
	v_fma_f32 v17, v16, v17, v16
	v_mul_f32_e32 v17, 0x3f4c422a, v17
	v_add_f32_e32 v17, v17, v17
	v_mul_f32_e32 v17, 0x3fb8aa3b, v17
	v_exp_f32_e32 v17, v17
	v_mul_f32_e32 v16, 0.5, v16
	v_add_f32_e32 v17, 1.0, v17
	v_rcp_f32_e32 v17, v17
	s_nop 0
	v_fma_f32 v17, v17, -2.0, 1.0
	v_add_f32_e32 v17, 1.0, v17
	v_mul_f32_e32 v16, v16, v17
	v_bfe_u32 v17, v16, 16, 1
	v_add3_u32 v18, v16, v17, s43
	v_or_b32_e32 v16, v22, v95
	v_lshlrev_b32_e32 v168, 1, v16
	v_lshl_add_u64 v[16:17], v[20:21], 0, v[168:169]
	global_store_short_d16_hi v[16:17], v18, off
	ds_read_b32 v16, v115
	s_waitcnt lgkmcnt(0)
	v_fmac_f32_e32 v19, v23, v16
	v_mul_f32_e32 v16, 0x3d372713, v19
	v_mul_f32_e32 v16, v19, v16
	v_fma_f32 v16, v19, v16, v19
	v_mul_f32_e32 v16, 0x3f4c422a, v16
	v_add_f32_e32 v16, v16, v16
	v_mul_f32_e32 v16, 0x3fb8aa3b, v16
	v_exp_f32_e32 v16, v16
	v_mul_f32_e32 v17, 0.5, v19
	v_add_f32_e32 v16, 1.0, v16
	v_rcp_f32_e32 v16, v16
	s_nop 0
	v_fma_f32 v16, v16, -2.0, 1.0
	v_add_f32_e32 v16, 1.0, v16
	v_mul_f32_e32 v16, v17, v16
	v_bfe_u32 v17, v16, 16, 1
	v_add3_u32 v18, v16, v17, s43
	v_or_b32_e32 v16, v22, v96
	v_lshlrev_b32_e32 v168, 1, v16
	v_lshl_add_u64 v[16:17], v[20:21], 0, v[168:169]
	global_store_short_d16_hi v[16:17], v18, off
	ds_read_b128 v[16:19], v128 offset:4352
	s_waitcnt lgkmcnt(0)
	v_mfma_f32_16x16x32_bf16 v[16:19], v[16:19], v[0:3], 0
	v_mfma_f32_16x16x32_bf16 v[16:19], v[24:27], v[4:7], v[16:19]
	ds_read_b128 v[24:27], v128 offset:4480
	s_waitcnt lgkmcnt(0)
	v_mfma_f32_16x16x32_bf16 v[16:19], v[24:27], v[8:11], v[16:19]
	ds_read_b128 v[24:27], v128 offset:4544
	s_waitcnt lgkmcnt(0)
	v_mfma_f32_16x16x32_bf16 v[16:19], v[24:27], v[12:15], v[16:19]
	ds_read_b32 v24, v116
	s_waitcnt lgkmcnt(0)
	s_nop 5
	v_fma_f32 v16, v23, v24, v16
	v_mul_f32_e32 v24, 0x3d372713, v16
	v_mul_f32_e32 v24, v16, v24
	v_fma_f32 v24, v16, v24, v16
	v_mul_f32_e32 v24, 0x3f4c422a, v24
	v_add_f32_e32 v24, v24, v24
	v_mul_f32_e32 v24, 0x3fb8aa3b, v24
	v_exp_f32_e32 v24, v24
	v_mul_f32_e32 v16, 0.5, v16
	v_add_f32_e32 v24, 1.0, v24
	v_rcp_f32_e32 v24, v24
	s_nop 0
	v_fma_f32 v24, v24, -2.0, 1.0
	v_add_f32_e32 v24, 1.0, v24
	v_mul_f32_e32 v16, v16, v24
	v_bfe_u32 v24, v16, 16, 1
	v_add3_u32 v16, v16, v24, s43
	v_or_b32_e32 v24, v22, v97
	v_lshlrev_b32_e32 v168, 1, v24
	v_lshl_add_u64 v[24:25], v[20:21], 0, v[168:169]
	global_store_short_d16_hi v[24:25], v16, off
	ds_read_b32 v16, v117
	s_waitcnt lgkmcnt(0)
	v_fma_f32 v16, v23, v16, v17
	v_mul_f32_e32 v17, 0x3d372713, v16
	v_mul_f32_e32 v17, v16, v17
	v_fma_f32 v17, v16, v17, v16
	v_mul_f32_e32 v17, 0x3f4c422a, v17
	v_add_f32_e32 v17, v17, v17
	v_mul_f32_e32 v17, 0x3fb8aa3b, v17
	v_exp_f32_e32 v17, v17
	v_mul_f32_e32 v16, 0.5, v16
	v_add_f32_e32 v17, 1.0, v17
	v_rcp_f32_e32 v17, v17
	s_nop 0
	v_fma_f32 v17, v17, -2.0, 1.0
	v_add_f32_e32 v17, 1.0, v17
	v_mul_f32_e32 v16, v16, v17
	v_bfe_u32 v17, v16, 16, 1
	v_add3_u32 v24, v16, v17, s43
	v_or_b32_e32 v16, v22, v98
	v_lshlrev_b32_e32 v168, 1, v16
	v_lshl_add_u64 v[16:17], v[20:21], 0, v[168:169]
	global_store_short_d16_hi v[16:17], v24, off
	ds_read_b32 v16, v118
	s_waitcnt lgkmcnt(0)
	v_fma_f32 v16, v23, v16, v18
	v_mul_f32_e32 v17, 0x3d372713, v16
	v_mul_f32_e32 v17, v16, v17
	v_fma_f32 v17, v16, v17, v16
	v_mul_f32_e32 v17, 0x3f4c422a, v17
	v_add_f32_e32 v17, v17, v17
	v_mul_f32_e32 v17, 0x3fb8aa3b, v17
	v_exp_f32_e32 v17, v17
	v_mul_f32_e32 v16, 0.5, v16
	v_add_f32_e32 v17, 1.0, v17
	v_rcp_f32_e32 v17, v17
	s_nop 0
	v_fma_f32 v17, v17, -2.0, 1.0
	v_add_f32_e32 v17, 1.0, v17
	v_mul_f32_e32 v16, v16, v17
	v_bfe_u32 v17, v16, 16, 1
	v_add3_u32 v18, v16, v17, s43
	v_or_b32_e32 v16, v22, v99
	v_lshlrev_b32_e32 v168, 1, v16
	v_lshl_add_u64 v[16:17], v[20:21], 0, v[168:169]
	global_store_short_d16_hi v[16:17], v18, off
	ds_read_b32 v16, v119
	s_waitcnt lgkmcnt(0)
	v_fmac_f32_e32 v19, v23, v16
	v_mul_f32_e32 v16, 0x3d372713, v19
	v_mul_f32_e32 v16, v19, v16
	v_fma_f32 v16, v19, v16, v19
	v_mul_f32_e32 v16, 0x3f4c422a, v16
	v_add_f32_e32 v16, v16, v16
	v_mul_f32_e32 v16, 0x3fb8aa3b, v16
	v_exp_f32_e32 v16, v16
	v_mul_f32_e32 v17, 0.5, v19
	v_add_f32_e32 v16, 1.0, v16
	v_rcp_f32_e32 v16, v16
	s_nop 0
	v_fma_f32 v16, v16, -2.0, 1.0
	v_add_f32_e32 v16, 1.0, v16
	v_mul_f32_e32 v16, v17, v16
	v_bfe_u32 v17, v16, 16, 1
	v_add3_u32 v18, v16, v17, s43
	v_or_b32_e32 v16, v22, v100
	v_lshlrev_b32_e32 v168, 1, v16
	v_lshl_add_u64 v[16:17], v[20:21], 0, v[168:169]
	global_store_short_d16_hi v[16:17], v18, off
	s_waitcnt lgkmcnt(0)
	v_mov_b32_e32 v16, v109
.LBB0_882:
	v_add_u32_e32 v17, s4, v110
	v_add_u32_e32 v18, 0x12000, v17
	ds_read_b128 v[24:27], v18
	v_add_u32_e32 v18, 0x12010, v17
	ds_read_b128 v[28:31], v18
	v_add_u32_e32 v39, 0x12070, v17
	s_addk_i32 s4, 0x200
	s_waitcnt lgkmcnt(1)
	v_pk_fma_f32 v[18:19], v[24:25], v[54:55], 0 op_sel_hi:[0,1,0]
	v_pk_fma_f32 v[18:19], v[24:25], v[56:57], v[18:19] op_sel:[1,0,0]
	v_pk_fma_f32 v[18:19], v[26:27], v[58:59], v[18:19] op_sel_hi:[0,1,1]
	v_pk_fma_f32 v[18:19], v[26:27], v[60:61], v[18:19] op_sel:[1,0,0]
	v_add_u32_e32 v24, 0x12020, v17
	ds_read_b128 v[24:27], v24
	s_waitcnt lgkmcnt(1)
	v_pk_fma_f32 v[18:19], v[28:29], v[62:63], v[18:19] op_sel_hi:[0,1,1]
	v_pk_fma_f32 v[18:19], v[28:29], v[64:65], v[18:19] op_sel:[1,0,0]
	v_add_u32_e32 v28, 0x12030, v17
	v_pk_fma_f32 v[18:19], v[30:31], v[68:69], v[18:19] op_sel_hi:[0,1,1]
	ds_read_b128 v[130:133], v28
	v_pk_fma_f32 v[18:19], v[30:31], v[70:71], v[18:19] op_sel:[1,0,0]
	s_waitcnt lgkmcnt(1)
	v_pk_fma_f32 v[18:19], v[24:25], v[72:73], v[18:19] op_sel_hi:[0,1,1]
	v_pk_fma_f32 v[18:19], v[24:25], v[74:75], v[18:19] op_sel:[1,0,0]
	v_pk_fma_f32 v[18:19], v[26:27], v[76:77], v[18:19] op_sel_hi:[0,1,1]
	v_pk_fma_f32 v[18:19], v[26:27], v[78:79], v[18:19] op_sel:[1,0,0]
	s_waitcnt lgkmcnt(0)
	v_pk_fma_f32 v[18:19], v[130:131], v[80:81], v[18:19] op_sel_hi:[0,1,1]
	v_pk_fma_f32 v[18:19], v[130:131], v[82:83], v[18:19] op_sel:[1,0,0]
	v_pk_mul_f32 v[28:29], v[52:53], v[66:67]
	v_pk_fma_f32 v[18:19], v[132:133], v[84:85], v[18:19] op_sel_hi:[0,1,1]
	v_pk_fma_f32 v[18:19], v[132:133], v[86:87], v[18:19] op_sel:[1,0,0]
	v_pk_fma_f32 v[24:25], v[88:89], v[66:67], v[28:29] op_sel:[0,0,1] op_sel_hi:[1,1,0]
	v_pk_fma_f32 v[26:27], v[88:89], v[66:67], v[28:29] op_sel:[0,0,1] op_sel_hi:[1,1,0] neg_lo:[0,0,1] neg_hi:[0,0,1]
	v_add_u32_e32 v28, 0x12050, v17
	v_mov_b32_e32 v25, v27
	v_pk_add_f32 v[18:19], v[24:25], v[18:19]
	s_cmp_lg_u32 s4, 0
	v_cvt_pk_bf16_f32 v24, v18, v19
	ds_write_b16_d16_hi v16, v24
	ds_write_b16 v16, v24 offset:128
	v_add_u32_e32 v24, 0x12040, v17
	ds_read_b128 v[24:27], v24
	ds_read_b128 v[28:31], v28
	ds_read_b128 v[130:133], v39
	v_add_u32_e32 v39, 0x120b0, v17
	s_waitcnt lgkmcnt(2)
	v_pk_fma_f32 v[66:67], v[24:25], v[54:55], 0 op_sel_hi:[0,1,0]
	v_pk_fma_f32 v[24:25], v[24:25], v[56:57], v[66:67] op_sel:[1,0,0]
	v_pk_mul_f32 v[66:67], v[52:53], v[18:19]
	v_pk_fma_f32 v[24:25], v[26:27], v[58:59], v[24:25] op_sel_hi:[0,1,1]
	v_pk_fma_f32 v[24:25], v[26:27], v[60:61], v[24:25] op_sel:[1,0,0]
	s_waitcnt lgkmcnt(1)
	v_pk_fma_f32 v[24:25], v[28:29], v[62:63], v[24:25] op_sel_hi:[0,1,1]
	v_pk_fma_f32 v[28:29], v[28:29], v[64:65], v[24:25] op_sel:[1,0,0]
	v_add_u32_e32 v24, 0x12060, v17
	ds_read_b128 v[24:27], v24
	v_pk_fma_f32 v[28:29], v[30:31], v[68:69], v[28:29] op_sel_hi:[0,1,1]
	v_pk_fma_f32 v[28:29], v[30:31], v[70:71], v[28:29] op_sel:[1,0,0]
	s_waitcnt lgkmcnt(0)
	v_pk_fma_f32 v[28:29], v[24:25], v[72:73], v[28:29] op_sel_hi:[0,1,1]
	v_pk_fma_f32 v[24:25], v[24:25], v[74:75], v[28:29] op_sel:[1,0,0]
	v_add_u32_e32 v28, 0x12090, v17
	v_pk_fma_f32 v[24:25], v[26:27], v[76:77], v[24:25] op_sel_hi:[0,1,1]
	v_pk_fma_f32 v[24:25], v[26:27], v[78:79], v[24:25] op_sel:[1,0,0]
	v_pk_fma_f32 v[24:25], v[130:131], v[80:81], v[24:25] op_sel_hi:[0,1,1]
	v_pk_fma_f32 v[24:25], v[130:131], v[82:83], v[24:25] op_sel:[1,0,0]
	v_pk_fma_f32 v[24:25], v[132:133], v[84:85], v[24:25] op_sel_hi:[0,1,1]
	v_pk_fma_f32 v[24:25], v[132:133], v[86:87], v[24:25] op_sel:[1,0,0]
	v_pk_fma_f32 v[26:27], v[88:89], v[18:19], v[66:67] op_sel:[0,0,1] op_sel_hi:[1,1,0]
	v_pk_fma_f32 v[18:19], v[88:89], v[18:19], v[66:67] op_sel:[0,0,1] op_sel_hi:[1,1,0] neg_lo:[0,0,1] neg_hi:[0,0,1]
	s_nop 0
	v_mov_b32_e32 v27, v19
	v_pk_add_f32 v[18:19], v[26:27], v[24:25]
	s_nop 0
	v_cvt_pk_bf16_f32 v24, v18, v19
	ds_write_b16_d16_hi v16, v24 offset:272
	ds_write_b16 v16, v24 offset:400
	v_add_u32_e32 v24, 0x12080, v17
	ds_read_b128 v[24:27], v24
	ds_read_b128 v[28:31], v28
	ds_read_b128 v[130:133], v39
	v_add_u32_e32 v39, 0x120f0, v17
	s_waitcnt lgkmcnt(2)
	v_pk_fma_f32 v[66:67], v[24:25], v[54:55], 0 op_sel_hi:[0,1,0]
	v_pk_fma_f32 v[24:25], v[24:25], v[56:57], v[66:67] op_sel:[1,0,0]
	v_pk_mul_f32 v[66:67], v[52:53], v[18:19]
	v_pk_fma_f32 v[24:25], v[26:27], v[58:59], v[24:25] op_sel_hi:[0,1,1]
	v_pk_fma_f32 v[24:25], v[26:27], v[60:61], v[24:25] op_sel:[1,0,0]
	s_waitcnt lgkmcnt(1)
	v_pk_fma_f32 v[24:25], v[28:29], v[62:63], v[24:25] op_sel_hi:[0,1,1]
	v_pk_fma_f32 v[28:29], v[28:29], v[64:65], v[24:25] op_sel:[1,0,0]
	v_add_u32_e32 v24, 0x120a0, v17
	ds_read_b128 v[24:27], v24
	v_pk_fma_f32 v[28:29], v[30:31], v[68:69], v[28:29] op_sel_hi:[0,1,1]
	v_pk_fma_f32 v[28:29], v[30:31], v[70:71], v[28:29] op_sel:[1,0,0]
	s_waitcnt lgkmcnt(0)
	v_pk_fma_f32 v[28:29], v[24:25], v[72:73], v[28:29] op_sel_hi:[0,1,1]
	v_pk_fma_f32 v[24:25], v[24:25], v[74:75], v[28:29] op_sel:[1,0,0]
	v_add_u32_e32 v28, 0x120d0, v17
	v_pk_fma_f32 v[24:25], v[26:27], v[76:77], v[24:25] op_sel_hi:[0,1,1]
	v_pk_fma_f32 v[24:25], v[26:27], v[78:79], v[24:25] op_sel:[1,0,0]
	v_pk_fma_f32 v[24:25], v[130:131], v[80:81], v[24:25] op_sel_hi:[0,1,1]
	v_pk_fma_f32 v[24:25], v[130:131], v[82:83], v[24:25] op_sel:[1,0,0]
	v_pk_fma_f32 v[24:25], v[132:133], v[84:85], v[24:25] op_sel_hi:[0,1,1]
	v_pk_fma_f32 v[24:25], v[132:133], v[86:87], v[24:25] op_sel:[1,0,0]
	v_pk_fma_f32 v[26:27], v[88:89], v[18:19], v[66:67] op_sel:[0,0,1] op_sel_hi:[1,1,0]
	v_pk_fma_f32 v[18:19], v[88:89], v[18:19], v[66:67] op_sel:[0,0,1] op_sel_hi:[1,1,0] neg_lo:[0,0,1] neg_hi:[0,0,1]
	s_nop 0
	v_mov_b32_e32 v27, v19
	v_pk_add_f32 v[18:19], v[26:27], v[24:25]
	s_nop 0
	v_cvt_pk_bf16_f32 v24, v18, v19
	ds_write_b16_d16_hi v16, v24 offset:544
	ds_write_b16 v16, v24 offset:672
	v_add_u32_e32 v24, 0x120c0, v17
	ds_read_b128 v[24:27], v24
	ds_read_b128 v[28:31], v28
	ds_read_b128 v[130:133], v39
	v_add_u32_e32 v39, 0x12130, v17
	s_waitcnt lgkmcnt(2)
	v_pk_fma_f32 v[66:67], v[24:25], v[54:55], 0 op_sel_hi:[0,1,0]
	v_pk_fma_f32 v[24:25], v[24:25], v[56:57], v[66:67] op_sel:[1,0,0]
	v_pk_mul_f32 v[66:67], v[52:53], v[18:19]
	v_pk_fma_f32 v[24:25], v[26:27], v[58:59], v[24:25] op_sel_hi:[0,1,1]
	v_pk_fma_f32 v[24:25], v[26:27], v[60:61], v[24:25] op_sel:[1,0,0]
	s_waitcnt lgkmcnt(1)
	v_pk_fma_f32 v[24:25], v[28:29], v[62:63], v[24:25] op_sel_hi:[0,1,1]
	v_pk_fma_f32 v[28:29], v[28:29], v[64:65], v[24:25] op_sel:[1,0,0]
	v_add_u32_e32 v24, 0x120e0, v17
	ds_read_b128 v[24:27], v24
	v_pk_fma_f32 v[28:29], v[30:31], v[68:69], v[28:29] op_sel_hi:[0,1,1]
	v_pk_fma_f32 v[28:29], v[30:31], v[70:71], v[28:29] op_sel:[1,0,0]
	s_waitcnt lgkmcnt(0)
	v_pk_fma_f32 v[28:29], v[24:25], v[72:73], v[28:29] op_sel_hi:[0,1,1]
	v_pk_fma_f32 v[24:25], v[24:25], v[74:75], v[28:29] op_sel:[1,0,0]
	v_add_u32_e32 v28, 0x12110, v17
	v_pk_fma_f32 v[24:25], v[26:27], v[76:77], v[24:25] op_sel_hi:[0,1,1]
	v_pk_fma_f32 v[24:25], v[26:27], v[78:79], v[24:25] op_sel:[1,0,0]
	v_pk_fma_f32 v[24:25], v[130:131], v[80:81], v[24:25] op_sel_hi:[0,1,1]
	v_pk_fma_f32 v[24:25], v[130:131], v[82:83], v[24:25] op_sel:[1,0,0]
	v_pk_fma_f32 v[24:25], v[132:133], v[84:85], v[24:25] op_sel_hi:[0,1,1]
	v_pk_fma_f32 v[24:25], v[132:133], v[86:87], v[24:25] op_sel:[1,0,0]
	v_pk_fma_f32 v[26:27], v[88:89], v[18:19], v[66:67] op_sel:[0,0,1] op_sel_hi:[1,1,0]
	v_pk_fma_f32 v[18:19], v[88:89], v[18:19], v[66:67] op_sel:[0,0,1] op_sel_hi:[1,1,0] neg_lo:[0,0,1] neg_hi:[0,0,1]
	s_nop 0
	v_mov_b32_e32 v27, v19
	v_pk_add_f32 v[18:19], v[26:27], v[24:25]
	s_nop 0
	v_cvt_pk_bf16_f32 v24, v18, v19
	ds_write_b16_d16_hi v16, v24 offset:816
	ds_write_b16 v16, v24 offset:944
	v_add_u32_e32 v24, 0x12100, v17
	ds_read_b128 v[24:27], v24
	ds_read_b128 v[28:31], v28
	ds_read_b128 v[130:133], v39
	v_add_u32_e32 v39, 0x12170, v17
	s_waitcnt lgkmcnt(2)
	v_pk_fma_f32 v[66:67], v[24:25], v[54:55], 0 op_sel_hi:[0,1,0]
	v_pk_fma_f32 v[24:25], v[24:25], v[56:57], v[66:67] op_sel:[1,0,0]
	v_pk_mul_f32 v[66:67], v[52:53], v[18:19]
	v_pk_fma_f32 v[24:25], v[26:27], v[58:59], v[24:25] op_sel_hi:[0,1,1]
	v_pk_fma_f32 v[24:25], v[26:27], v[60:61], v[24:25] op_sel:[1,0,0]
	s_waitcnt lgkmcnt(1)
	v_pk_fma_f32 v[24:25], v[28:29], v[62:63], v[24:25] op_sel_hi:[0,1,1]
	v_pk_fma_f32 v[28:29], v[28:29], v[64:65], v[24:25] op_sel:[1,0,0]
	v_add_u32_e32 v24, 0x12120, v17
	ds_read_b128 v[24:27], v24
	v_pk_fma_f32 v[28:29], v[30:31], v[68:69], v[28:29] op_sel_hi:[0,1,1]
	v_pk_fma_f32 v[28:29], v[30:31], v[70:71], v[28:29] op_sel:[1,0,0]
	s_waitcnt lgkmcnt(0)
	v_pk_fma_f32 v[28:29], v[24:25], v[72:73], v[28:29] op_sel_hi:[0,1,1]
	v_pk_fma_f32 v[24:25], v[24:25], v[74:75], v[28:29] op_sel:[1,0,0]
	v_add_u32_e32 v28, 0x12150, v17
	v_pk_fma_f32 v[24:25], v[26:27], v[76:77], v[24:25] op_sel_hi:[0,1,1]
	v_pk_fma_f32 v[24:25], v[26:27], v[78:79], v[24:25] op_sel:[1,0,0]
	v_pk_fma_f32 v[24:25], v[130:131], v[80:81], v[24:25] op_sel_hi:[0,1,1]
	v_pk_fma_f32 v[24:25], v[130:131], v[82:83], v[24:25] op_sel:[1,0,0]
	v_pk_fma_f32 v[24:25], v[132:133], v[84:85], v[24:25] op_sel_hi:[0,1,1]
	v_pk_fma_f32 v[24:25], v[132:133], v[86:87], v[24:25] op_sel:[1,0,0]
	v_pk_fma_f32 v[26:27], v[88:89], v[18:19], v[66:67] op_sel:[0,0,1] op_sel_hi:[1,1,0]
	v_pk_fma_f32 v[18:19], v[88:89], v[18:19], v[66:67] op_sel:[0,0,1] op_sel_hi:[1,1,0] neg_lo:[0,0,1] neg_hi:[0,0,1]
	s_nop 0
	v_mov_b32_e32 v27, v19
	v_pk_add_f32 v[18:19], v[26:27], v[24:25]
	s_nop 0
	v_cvt_pk_bf16_f32 v24, v18, v19
	ds_write_b16_d16_hi v16, v24 offset:1088
	ds_write_b16 v16, v24 offset:1216
	v_add_u32_e32 v24, 0x12140, v17
	ds_read_b128 v[24:27], v24
	ds_read_b128 v[28:31], v28
	ds_read_b128 v[130:133], v39
	v_add_u32_e32 v39, 0x121b0, v17
	s_waitcnt lgkmcnt(2)
	v_pk_fma_f32 v[66:67], v[24:25], v[54:55], 0 op_sel_hi:[0,1,0]
	v_pk_fma_f32 v[24:25], v[24:25], v[56:57], v[66:67] op_sel:[1,0,0]
	v_pk_mul_f32 v[66:67], v[52:53], v[18:19]
	v_pk_fma_f32 v[24:25], v[26:27], v[58:59], v[24:25] op_sel_hi:[0,1,1]
	v_pk_fma_f32 v[24:25], v[26:27], v[60:61], v[24:25] op_sel:[1,0,0]
	s_waitcnt lgkmcnt(1)
	v_pk_fma_f32 v[24:25], v[28:29], v[62:63], v[24:25] op_sel_hi:[0,1,1]
	v_pk_fma_f32 v[28:29], v[28:29], v[64:65], v[24:25] op_sel:[1,0,0]
	v_add_u32_e32 v24, 0x12160, v17
	ds_read_b128 v[24:27], v24
	v_pk_fma_f32 v[28:29], v[30:31], v[68:69], v[28:29] op_sel_hi:[0,1,1]
	v_pk_fma_f32 v[28:29], v[30:31], v[70:71], v[28:29] op_sel:[1,0,0]
	s_waitcnt lgkmcnt(0)
	v_pk_fma_f32 v[28:29], v[24:25], v[72:73], v[28:29] op_sel_hi:[0,1,1]
	v_pk_fma_f32 v[24:25], v[24:25], v[74:75], v[28:29] op_sel:[1,0,0]
	v_add_u32_e32 v28, 0x12190, v17
	v_pk_fma_f32 v[24:25], v[26:27], v[76:77], v[24:25] op_sel_hi:[0,1,1]
	v_pk_fma_f32 v[24:25], v[26:27], v[78:79], v[24:25] op_sel:[1,0,0]
	v_pk_fma_f32 v[24:25], v[130:131], v[80:81], v[24:25] op_sel_hi:[0,1,1]
	v_pk_fma_f32 v[24:25], v[130:131], v[82:83], v[24:25] op_sel:[1,0,0]
	v_pk_fma_f32 v[24:25], v[132:133], v[84:85], v[24:25] op_sel_hi:[0,1,1]
	v_pk_fma_f32 v[24:25], v[132:133], v[86:87], v[24:25] op_sel:[1,0,0]
	v_pk_fma_f32 v[26:27], v[88:89], v[18:19], v[66:67] op_sel:[0,0,1] op_sel_hi:[1,1,0]
	v_pk_fma_f32 v[18:19], v[88:89], v[18:19], v[66:67] op_sel:[0,0,1] op_sel_hi:[1,1,0] neg_lo:[0,0,1] neg_hi:[0,0,1]
	s_nop 0
	v_mov_b32_e32 v27, v19
	v_pk_add_f32 v[18:19], v[26:27], v[24:25]
	s_nop 0
	v_cvt_pk_bf16_f32 v24, v18, v19
	ds_write_b16_d16_hi v16, v24 offset:1360
	ds_write_b16 v16, v24 offset:1488
	v_add_u32_e32 v24, 0x12180, v17
	ds_read_b128 v[24:27], v24
	ds_read_b128 v[28:31], v28
	ds_read_b128 v[130:133], v39
	s_waitcnt lgkmcnt(2)
	v_pk_fma_f32 v[66:67], v[24:25], v[54:55], 0 op_sel_hi:[0,1,0]
	v_pk_fma_f32 v[24:25], v[24:25], v[56:57], v[66:67] op_sel:[1,0,0]
	v_pk_mul_f32 v[66:67], v[52:53], v[18:19]
	v_pk_fma_f32 v[24:25], v[26:27], v[58:59], v[24:25] op_sel_hi:[0,1,1]
	v_pk_fma_f32 v[24:25], v[26:27], v[60:61], v[24:25] op_sel:[1,0,0]
	s_waitcnt lgkmcnt(1)
	v_pk_fma_f32 v[24:25], v[28:29], v[62:63], v[24:25] op_sel_hi:[0,1,1]
	v_pk_fma_f32 v[28:29], v[28:29], v[64:65], v[24:25] op_sel:[1,0,0]
	v_add_u32_e32 v24, 0x121a0, v17
	ds_read_b128 v[24:27], v24
	v_pk_fma_f32 v[28:29], v[30:31], v[68:69], v[28:29] op_sel_hi:[0,1,1]
	v_pk_fma_f32 v[28:29], v[30:31], v[70:71], v[28:29] op_sel:[1,0,0]
	s_waitcnt lgkmcnt(0)
	v_pk_fma_f32 v[28:29], v[24:25], v[72:73], v[28:29] op_sel_hi:[0,1,1]
	v_pk_fma_f32 v[24:25], v[24:25], v[74:75], v[28:29] op_sel:[1,0,0]
	v_add_u32_e32 v28, 0x121d0, v17
	v_pk_fma_f32 v[24:25], v[26:27], v[76:77], v[24:25] op_sel_hi:[0,1,1]
	v_pk_fma_f32 v[24:25], v[26:27], v[78:79], v[24:25] op_sel:[1,0,0]
	v_pk_fma_f32 v[24:25], v[130:131], v[80:81], v[24:25] op_sel_hi:[0,1,1]
	v_pk_fma_f32 v[24:25], v[130:131], v[82:83], v[24:25] op_sel:[1,0,0]
	v_pk_fma_f32 v[24:25], v[132:133], v[84:85], v[24:25] op_sel_hi:[0,1,1]
	v_pk_fma_f32 v[24:25], v[132:133], v[86:87], v[24:25] op_sel:[1,0,0]
	v_pk_fma_f32 v[26:27], v[88:89], v[18:19], v[66:67] op_sel:[0,0,1] op_sel_hi:[1,1,0]
	v_pk_fma_f32 v[18:19], v[88:89], v[18:19], v[66:67] op_sel:[0,0,1] op_sel_hi:[1,1,0] neg_lo:[0,0,1] neg_hi:[0,0,1]
	s_nop 0
	v_mov_b32_e32 v27, v19
	v_pk_add_f32 v[18:19], v[26:27], v[24:25]
	s_nop 0
	v_cvt_pk_bf16_f32 v24, v18, v19
	ds_write_b16_d16_hi v16, v24 offset:1632
	ds_write_b16 v16, v24 offset:1760
	v_add_u32_e32 v24, 0x121c0, v17
	ds_read_b128 v[24:27], v24
	ds_read_b128 v[28:31], v28
	s_waitcnt lgkmcnt(1)
	v_pk_fma_f32 v[66:67], v[24:25], v[54:55], 0 op_sel_hi:[0,1,0]
	v_pk_fma_f32 v[24:25], v[24:25], v[56:57], v[66:67] op_sel:[1,0,0]
	v_pk_mul_f32 v[66:67], v[52:53], v[18:19]
	v_pk_fma_f32 v[24:25], v[26:27], v[58:59], v[24:25] op_sel_hi:[0,1,1]
	v_pk_fma_f32 v[24:25], v[26:27], v[60:61], v[24:25] op_sel:[1,0,0]
	s_waitcnt lgkmcnt(0)
	v_pk_fma_f32 v[24:25], v[28:29], v[62:63], v[24:25] op_sel_hi:[0,1,1]
	v_pk_fma_f32 v[28:29], v[28:29], v[64:65], v[24:25] op_sel:[1,0,0]
	v_add_u32_e32 v24, 0x121e0, v17
	ds_read_b128 v[24:27], v24
	v_add_u32_e32 v17, 0x121f0, v17
	v_pk_fma_f32 v[28:29], v[30:31], v[68:69], v[28:29] op_sel_hi:[0,1,1]
	ds_read_b128 v[130:133], v17
	v_pk_fma_f32 v[28:29], v[30:31], v[70:71], v[28:29] op_sel:[1,0,0]
	s_waitcnt lgkmcnt(1)
	v_pk_fma_f32 v[28:29], v[24:25], v[72:73], v[28:29] op_sel_hi:[0,1,1]
	v_pk_fma_f32 v[24:25], v[24:25], v[74:75], v[28:29] op_sel:[1,0,0]
	s_nop 0
	v_pk_fma_f32 v[24:25], v[26:27], v[76:77], v[24:25] op_sel_hi:[0,1,1]
	v_pk_fma_f32 v[24:25], v[26:27], v[78:79], v[24:25] op_sel:[1,0,0]
	s_waitcnt lgkmcnt(0)
	v_pk_fma_f32 v[24:25], v[130:131], v[80:81], v[24:25] op_sel_hi:[0,1,1]
	v_pk_fma_f32 v[24:25], v[130:131], v[82:83], v[24:25] op_sel:[1,0,0]
	v_pk_fma_f32 v[24:25], v[132:133], v[84:85], v[24:25] op_sel_hi:[0,1,1]
	v_pk_fma_f32 v[24:25], v[132:133], v[86:87], v[24:25] op_sel:[1,0,0]
	v_pk_fma_f32 v[26:27], v[88:89], v[18:19], v[66:67] op_sel:[0,0,1] op_sel_hi:[1,1,0]
	v_pk_fma_f32 v[18:19], v[88:89], v[18:19], v[66:67] op_sel:[0,0,1] op_sel_hi:[1,1,0] neg_lo:[0,0,1] neg_hi:[0,0,1]
	s_nop 0
	v_mov_b32_e32 v27, v19
	v_pk_add_f32 v[66:67], v[26:27], v[24:25]
	s_nop 0
	v_cvt_pk_bf16_f32 v17, v66, v67
	ds_write_b16_d16_hi v16, v17 offset:1904
	ds_write_b16 v16, v17 offset:2032
	v_add_u32_e32 v16, 0x880, v16
	s_cbranch_scc1 .LBB0_882
	s_waitcnt lgkmcnt(0)
	ds_read_b128 v[16:19], v128
	ds_read_b128 v[24:27], v128 offset:64
	v_add_u32_e32 v33, s19, v33
	s_movk_i32 s2, 0xfff
	v_cmp_lt_i32_e32 vcc, s2, v33
	s_or_b64 s[22:23], vcc, s[22:23]
	s_waitcnt lgkmcnt(1)
	v_mfma_f32_16x16x32_bf16 v[16:19], v[16:19], v[0:3], 0
	s_waitcnt lgkmcnt(0)
	v_mfma_f32_16x16x32_bf16 v[16:19], v[24:27], v[4:7], v[16:19]
	ds_read_b128 v[24:27], v128 offset:128
	s_waitcnt lgkmcnt(0)
	v_mfma_f32_16x16x32_bf16 v[16:19], v[24:27], v[8:11], v[16:19]
	ds_read_b128 v[24:27], v128 offset:192
	s_waitcnt lgkmcnt(0)
	v_mfma_f32_16x16x32_bf16 v[16:19], v[24:27], v[12:15], v[16:19]
	ds_read_b32 v24, v120
	s_waitcnt lgkmcnt(0)
	s_nop 5
	v_fma_f32 v16, v23, v24, v16
	v_mul_f32_e32 v24, 0x3d372713, v16
	v_mul_f32_e32 v24, v16, v24
	v_fma_f32 v24, v16, v24, v16
	v_mul_f32_e32 v24, 0x3f4c422a, v24
	v_add_f32_e32 v24, v24, v24
	v_mul_f32_e32 v24, 0x3fb8aa3b, v24
	v_exp_f32_e32 v24, v24
	v_mul_f32_e32 v16, 0.5, v16
	v_add_f32_e32 v24, 1.0, v24
	v_rcp_f32_e32 v24, v24
	s_nop 0
	v_fma_f32 v24, v24, -2.0, 1.0
	v_add_f32_e32 v24, 1.0, v24
	v_mul_f32_e32 v16, v16, v24
	v_bfe_u32 v24, v16, 16, 1
	v_add3_u32 v16, v16, v24, s43
	v_or_b32_e32 v24, v22, v101
	v_lshlrev_b32_e32 v168, 1, v24
	v_lshl_add_u64 v[24:25], v[20:21], 0, v[168:169]
	global_store_short_d16_hi v[24:25], v16, off
	ds_read_b32 v16, v121
	s_waitcnt lgkmcnt(0)
	v_fma_f32 v16, v23, v16, v17
	v_mul_f32_e32 v17, 0x3d372713, v16
	v_mul_f32_e32 v17, v16, v17
	v_fma_f32 v17, v16, v17, v16
	v_mul_f32_e32 v17, 0x3f4c422a, v17
	v_add_f32_e32 v17, v17, v17
	v_mul_f32_e32 v17, 0x3fb8aa3b, v17
	v_exp_f32_e32 v17, v17
	v_mul_f32_e32 v16, 0.5, v16
	v_add_f32_e32 v17, 1.0, v17
	v_rcp_f32_e32 v17, v17
	s_nop 0
	v_fma_f32 v17, v17, -2.0, 1.0
	v_add_f32_e32 v17, 1.0, v17
	v_mul_f32_e32 v16, v16, v17
	v_bfe_u32 v17, v16, 16, 1
	v_add3_u32 v24, v16, v17, s43
	v_or_b32_e32 v16, v22, v102
	v_lshlrev_b32_e32 v168, 1, v16
	v_lshl_add_u64 v[16:17], v[20:21], 0, v[168:169]
	global_store_short_d16_hi v[16:17], v24, off
	ds_read_b32 v16, v122
	s_waitcnt lgkmcnt(0)
	v_fma_f32 v16, v23, v16, v18
	v_mul_f32_e32 v17, 0x3d372713, v16
	v_mul_f32_e32 v17, v16, v17
	v_fma_f32 v17, v16, v17, v16
	v_mul_f32_e32 v17, 0x3f4c422a, v17
	v_add_f32_e32 v17, v17, v17
	v_mul_f32_e32 v17, 0x3fb8aa3b, v17
	v_exp_f32_e32 v17, v17
	v_mul_f32_e32 v16, 0.5, v16
	v_add_f32_e32 v17, 1.0, v17
	v_rcp_f32_e32 v17, v17
	s_nop 0
	v_fma_f32 v17, v17, -2.0, 1.0
	v_add_f32_e32 v17, 1.0, v17
	v_mul_f32_e32 v16, v16, v17
	v_bfe_u32 v17, v16, 16, 1
	v_add3_u32 v18, v16, v17, s43
	v_or_b32_e32 v16, v22, v103
	v_lshlrev_b32_e32 v168, 1, v16
	v_lshl_add_u64 v[16:17], v[20:21], 0, v[168:169]
	global_store_short_d16_hi v[16:17], v18, off
	ds_read_b32 v16, v123
	s_waitcnt lgkmcnt(0)
	v_fmac_f32_e32 v19, v23, v16
	v_mul_f32_e32 v16, 0x3d372713, v19
	v_mul_f32_e32 v16, v19, v16
	v_fma_f32 v16, v19, v16, v19
	v_mul_f32_e32 v16, 0x3f4c422a, v16
	v_add_f32_e32 v16, v16, v16
	v_mul_f32_e32 v16, 0x3fb8aa3b, v16
	v_exp_f32_e32 v16, v16
	v_mul_f32_e32 v17, 0.5, v19
	v_add_f32_e32 v16, 1.0, v16
	v_rcp_f32_e32 v16, v16
	s_nop 0
	v_fma_f32 v16, v16, -2.0, 1.0
	v_add_f32_e32 v16, 1.0, v16
	v_mul_f32_e32 v16, v17, v16
	v_bfe_u32 v17, v16, 16, 1
	v_add3_u32 v18, v16, v17, s43
	v_or_b32_e32 v16, v22, v104
	v_lshlrev_b32_e32 v168, 1, v16
	v_lshl_add_u64 v[16:17], v[20:21], 0, v[168:169]
	global_store_short_d16_hi v[16:17], v18, off
	ds_read_b128 v[16:19], v128 offset:4352
	s_waitcnt lgkmcnt(0)
	v_mfma_f32_16x16x32_bf16 v[0:3], v[16:19], v[0:3], 0
	ds_read_b128 v[16:19], v128 offset:4416
	s_waitcnt lgkmcnt(0)
	v_mfma_f32_16x16x32_bf16 v[0:3], v[16:19], v[4:7], v[0:3]
	ds_read_b128 v[4:7], v128 offset:4480
	s_waitcnt lgkmcnt(0)
	v_mfma_f32_16x16x32_bf16 v[0:3], v[4:7], v[8:11], v[0:3]
	ds_read_b128 v[4:7], v128 offset:4544
	s_waitcnt lgkmcnt(0)
	v_mfma_f32_16x16x32_bf16 v[0:3], v[4:7], v[12:15], v[0:3]
	ds_read_b32 v4, v124
	s_waitcnt lgkmcnt(0)
	s_nop 5
	v_fma_f32 v0, v23, v4, v0
	v_mul_f32_e32 v4, 0x3d372713, v0
	v_mul_f32_e32 v4, v0, v4
	v_fma_f32 v4, v0, v4, v0
	v_mul_f32_e32 v4, 0x3f4c422a, v4
	v_add_f32_e32 v4, v4, v4
	v_mul_f32_e32 v4, 0x3fb8aa3b, v4
	v_exp_f32_e32 v4, v4
	v_mul_f32_e32 v0, 0.5, v0
	v_add_f32_e32 v4, 1.0, v4
	v_rcp_f32_e32 v4, v4
	s_nop 0
	v_fma_f32 v4, v4, -2.0, 1.0
	v_add_f32_e32 v4, 1.0, v4
	v_mul_f32_e32 v0, v0, v4
	v_bfe_u32 v4, v0, 16, 1
	v_add3_u32 v0, v0, v4, s43
	v_or_b32_e32 v4, v22, v105
	v_lshlrev_b32_e32 v168, 1, v4
	v_lshl_add_u64 v[4:5], v[20:21], 0, v[168:169]
	global_store_short_d16_hi v[4:5], v0, off
	ds_read_b32 v0, v125
	s_waitcnt lgkmcnt(0)
	v_fma_f32 v0, v23, v0, v1
	v_mul_f32_e32 v1, 0x3d372713, v0
	v_mul_f32_e32 v1, v0, v1
	v_fma_f32 v1, v0, v1, v0
	v_mul_f32_e32 v1, 0x3f4c422a, v1
	v_add_f32_e32 v1, v1, v1
	v_mul_f32_e32 v1, 0x3fb8aa3b, v1
	v_exp_f32_e32 v1, v1
	v_mul_f32_e32 v0, 0.5, v0
	v_add_f32_e32 v1, 1.0, v1
	v_rcp_f32_e32 v1, v1
	s_nop 0
	v_fma_f32 v1, v1, -2.0, 1.0
	v_add_f32_e32 v1, 1.0, v1
	v_mul_f32_e32 v0, v0, v1
	v_bfe_u32 v1, v0, 16, 1
	v_add3_u32 v4, v0, v1, s43
	v_or_b32_e32 v0, v22, v106
	v_lshlrev_b32_e32 v168, 1, v0
	v_lshl_add_u64 v[0:1], v[20:21], 0, v[168:169]
	global_store_short_d16_hi v[0:1], v4, off
	ds_read_b32 v0, v126
	s_waitcnt lgkmcnt(0)
	v_fma_f32 v0, v23, v0, v2
	v_mul_f32_e32 v1, 0x3d372713, v0
	v_mul_f32_e32 v1, v0, v1
	v_fma_f32 v1, v0, v1, v0
	v_mul_f32_e32 v1, 0x3f4c422a, v1
	v_add_f32_e32 v1, v1, v1
	v_mul_f32_e32 v1, 0x3fb8aa3b, v1
	v_exp_f32_e32 v1, v1
	v_mul_f32_e32 v0, 0.5, v0
	v_add_f32_e32 v1, 1.0, v1
	v_rcp_f32_e32 v1, v1
	s_nop 0
	v_fma_f32 v1, v1, -2.0, 1.0
	v_add_f32_e32 v1, 1.0, v1
	v_mul_f32_e32 v0, v0, v1
	v_bfe_u32 v1, v0, 16, 1
	v_add3_u32 v2, v0, v1, s43
	v_or_b32_e32 v0, v22, v107
	v_lshlrev_b32_e32 v168, 1, v0
	v_lshl_add_u64 v[0:1], v[20:21], 0, v[168:169]
	global_store_short_d16_hi v[0:1], v2, off
	ds_read_b32 v0, v127
	s_waitcnt lgkmcnt(0)
	v_fmac_f32_e32 v3, v23, v0
	v_mul_f32_e32 v0, 0x3d372713, v3
	v_mul_f32_e32 v0, v3, v0
	v_fma_f32 v0, v3, v0, v3
	v_mul_f32_e32 v0, 0x3f4c422a, v0
	v_add_f32_e32 v0, v0, v0
	v_mul_f32_e32 v0, 0x3fb8aa3b, v0
	v_exp_f32_e32 v0, v0
	v_mul_f32_e32 v1, 0.5, v3
	v_add_f32_e32 v0, 1.0, v0
	v_rcp_f32_e32 v0, v0
	s_nop 0
	v_fma_f32 v0, v0, -2.0, 1.0
	v_add_f32_e32 v0, 1.0, v0
	v_mul_f32_e32 v0, v1, v0
	v_bfe_u32 v1, v0, 16, 1
	v_add3_u32 v2, v0, v1, s43
	v_or_b32_e32 v0, v22, v108
	v_lshlrev_b32_e32 v168, 1, v0
	v_lshl_add_u64 v[0:1], v[20:21], 0, v[168:169]
	global_store_short_d16_hi v[0:1], v2, off
	s_waitcnt lgkmcnt(0)
	s_andn2_b64 exec, exec, s[22:23]
	s_cbranch_execnz .LBB0_859
